# strategy: static priority instead of per-phase s_setprio flips - all 112 s_setprio flip instructions removed from the five GEMM K-loops (no inserted issue slots between MFMA blocks); A/B showed a stat
# speedup vs baseline: 1.0026x; 1.0026x over previous
; #define GP_STAGE(bufoff, gbase, voff) do { _Pragma("unroll") for (int _i = 0; _i < 2; ++_i) \
;         __builtin_amdgcn_global_load_lds((const unsigned*)((const char*)(gbase) + (voff)[_i]), (LAS unsigned*)(lds + (bufoff) + ldsw + _i * 8192), 16, 0, 0); } while (0)
; #define GP_LDA(dst, b, h) do { _Pragma("unroll") for (int m = 0; m < 4; ++m) _Pragma("unroll") for (int k = 0; k < 2; ++k) dst[m][k] = *(const LAS bf16x8*)(lds + GP_SA(b, h) + aoff + m * 2048 + k * 1024); } while (0)
; #define GP_LDB(dst, b, h) do { _Pragma("unroll") for (int n = 0; n < 2; ++n) _Pragma("unroll") for (int k = 0; k < 2; ++k) dst[n][k] = *(const LAS bf16x8*)(lds + GP_SB(b, h) + boff + n * 2048 + k * 1024); } while (0)
; #define GP_WAIT_V(n) asm volatile("s_waitcnt vmcnt(" #n ")" ::: "memory")
; #define GP_WAIT_L(n) asm volatile("s_waitcnt lgkmcnt(" #n ")" ::: "memory")
; template <class Epi, class Sched>
; __device__ __forceinline__ void gemm_phase(LAS unsigned char* lds, const int lda, const int ldb, const int K, const Sched& S, const Epi& E, const int widx) {
;     ...
;         for (int t = 0; t < nt; t += 2) {
;             const bool last = (t == nt - 2);
;             const char* a1 = cA + (size_t)(t + 1) * kstep;
;             const char* a2 = last ? nA : cA + (size_t)(t + 2) * kstep; const char* b2 = last ? nB : cB + (size_t)(t + 2) * kstep;
;             const char* a3 = a2 + kstep; const char* b3 = b2 + kstep;
;             GP_LDB(B0, 0, 0); GP_LDB(B1, 0, 1); GP_SCHED; GP_LDA(At, 0, 0); GP_STAGE(GP_SA(1, 1), a1 + hstepA, voffA);
;             GP_WAIT_V(8); GP_WAIT_L(0); GP_BAR; GP_MMA(0, 0, At, B0); GP_MMA(0, 1, At, B1); GP_BAR; GP_SCHED;
;             GP_LDA(At, 0, 1); GP_STAGE(GP_SB(0, 0), b2, voffB); GP_STAGE(GP_SB(0, 1), b2 + hstepB, voffB); GP_STAGE(GP_SA(0, 0), a2, voffA);
;             GP_WAIT_V(8); GP_WAIT_L(0); GP_BAR; GP_MMA(1, 0, At, B0); GP_MMA(1, 1, At, B1); GP_BAR; GP_SCHED;
;             GP_LDB(B0, 1, 0); GP_LDB(B1, 1, 1); GP_SCHED; GP_LDA(At, 1, 0); GP_STAGE(GP_SA(0, 1), a2 + hstepA, voffA);
;             GP_WAIT_V(8); GP_WAIT_L(0); GP_BAR; GP_MMA(0, 0, At, B0); GP_MMA(0, 1, At, B1); GP_BAR; GP_SCHED;
;             GP_LDA(At, 1, 1); GP_STAGE(GP_SB(1, 0), b3, voffB); GP_STAGE(GP_SB(1, 1), b3 + hstepB, voffB); GP_STAGE(GP_SA(1, 0), a3, voffA);
;             GP_WAIT_V(8); GP_WAIT_L(0); GP_BAR; GP_MMA(1, 0, At, B0); GP_MMA(1, 1, At, B1); GP_BAR; GP_SCHED;
.LBB0_135:
	v_add_u32_e32 v144, s55, v167
	ds_read_b128 v[128:131], v144
	ds_read_b128 v[132:135], v144 offset:1024
	ds_read_b128 v[136:139], v144 offset:2048
	ds_read_b128 v[174:177], v144 offset:3072
	v_add_u32_e32 v144, s79, v167
	ds_read_b128 v[178:181], v144
	ds_read_b128 v[182:185], v144 offset:1024
	ds_read_b128 v[186:189], v144 offset:2048
	ds_read_b128 v[190:193], v144 offset:3072
	s_add_u32 s30, s4, 0xfffc0080
	s_addc_u32 s31, s5, -1
	s_cmp_eq_u32 s83, 12
	s_cselect_b32 s31, s35, s31
	s_cselect_b32 s30, s42, s30
	s_cselect_b32 s93, s43, s82
	s_cselect_b32 s92, s64, s81
	s_add_i32 m0, s85, 0xc000
	ds_read_b128 v[198:201], v196
	ds_read_b128 v[202:205], v196 offset:1024
	ds_read_b128 v[206:209], v196 offset:2048
	ds_read_b128 v[210:213], v196 offset:3072
	ds_read_b128 v[214:217], v196 offset:4096
	ds_read_b128 v[218:221], v196 offset:5120
	ds_read_b128 v[222:225], v196 offset:6144
	ds_read_b128 v[226:229], v196 offset:7168
	global_load_lds_dwordx4 v170, s[4:5]
	s_add_i32 m0, s85, 0xe000
	s_nop 0
	global_load_lds_dwordx4 v172, s[4:5]
	s_waitcnt vmcnt(8)
	s_waitcnt lgkmcnt(0)
	s_barrier
	s_waitcnt lgkmcnt(0)
	v_mfma_f32_16x16x32_bf16 v[116:119], v[128:131], v[198:201], v[116:119]
	v_mfma_f32_16x16x32_bf16 v[124:127], v[136:139], v[198:201], v[124:127]
	v_mfma_f32_16x16x32_bf16 v[84:87], v[128:131], v[206:209], v[84:87]
	v_mfma_f32_16x16x32_bf16 v[108:111], v[136:139], v[206:209], v[108:111]
	v_mfma_f32_16x16x32_bf16 v[76:79], v[128:131], v[214:217], v[76:79]
	v_mfma_f32_16x16x32_bf16 v[100:103], v[136:139], v[214:217], v[100:103]
	v_mfma_f32_16x16x32_bf16 v[68:71], v[128:131], v[222:225], v[68:71]
	v_mfma_f32_16x16x32_bf16 v[92:95], v[136:139], v[222:225], v[92:95]
	v_mfma_f32_16x16x32_bf16 v[116:119], v[132:135], v[202:205], v[116:119]
	v_mfma_f32_16x16x32_bf16 v[124:127], v[174:177], v[202:205], v[124:127]
	v_mfma_f32_16x16x32_bf16 v[84:87], v[132:135], v[210:213], v[84:87]
	v_mfma_f32_16x16x32_bf16 v[108:111], v[174:177], v[210:213], v[108:111]
	v_mfma_f32_16x16x32_bf16 v[76:79], v[132:135], v[218:221], v[76:79]
	v_mfma_f32_16x16x32_bf16 v[100:103], v[174:177], v[218:221], v[100:103]
	v_mfma_f32_16x16x32_bf16 v[68:71], v[132:135], v[226:229], v[68:71]
	v_mfma_f32_16x16x32_bf16 v[92:95], v[174:177], v[226:229], v[92:95]
	v_mfma_f32_16x16x32_bf16 v[120:123], v[178:181], v[198:201], v[120:123]
	v_mfma_f32_16x16x32_bf16 v[112:115], v[186:189], v[198:201], v[112:115]
	v_mfma_f32_16x16x32_bf16 v[104:107], v[178:181], v[206:209], v[104:107]
	v_mfma_f32_16x16x32_bf16 v[80:83], v[186:189], v[206:209], v[80:83]
	v_mfma_f32_16x16x32_bf16 v[96:99], v[178:181], v[214:217], v[96:99]
	v_mfma_f32_16x16x32_bf16 v[72:75], v[186:189], v[214:217], v[72:75]
	v_mfma_f32_16x16x32_bf16 v[88:91], v[178:181], v[222:225], v[88:91]
	v_mfma_f32_16x16x32_bf16 v[64:67], v[186:189], v[222:225], v[64:67]
	v_mfma_f32_16x16x32_bf16 v[120:123], v[182:185], v[202:205], v[120:123]
	v_mfma_f32_16x16x32_bf16 v[112:115], v[190:193], v[202:205], v[112:115]
	v_mfma_f32_16x16x32_bf16 v[104:107], v[182:185], v[210:213], v[104:107]
	v_mfma_f32_16x16x32_bf16 v[80:83], v[190:193], v[210:213], v[80:83]
	v_mfma_f32_16x16x32_bf16 v[96:99], v[182:185], v[218:221], v[96:99]
	v_mfma_f32_16x16x32_bf16 v[72:75], v[190:193], v[218:221], v[72:75]
	v_mfma_f32_16x16x32_bf16 v[88:91], v[182:185], v[226:229], v[88:91]
	v_mfma_f32_16x16x32_bf16 v[64:67], v[190:193], v[226:229], v[64:67]
	s_barrier
	s_add_i32 s86, s55, s97
	s_mov_b32 m0, s86
	ds_read_b128 v[198:201], v196 offset:16384
	ds_read_b128 v[202:205], v196 offset:17408
	ds_read_b128 v[206:209], v196 offset:18432
	ds_read_b128 v[210:213], v196 offset:19456
	ds_read_b128 v[214:217], v196 offset:20480
	ds_read_b128 v[218:221], v196 offset:21504
	ds_read_b128 v[222:225], v196 offset:22528
	ds_read_b128 v[226:229], v196 offset:23552
	global_load_lds_dwordx4 v140, s[92:93]
	s_add_i32 m0, s86, 0x2000
	s_add_u32 s86, s92, 0x40000
	s_addc_u32 s87, s93, 0
	s_add_i32 s88, s79, s97
	global_load_lds_dwordx4 v142, s[92:93]
	s_mov_b32 m0, s88
	s_nop 0
	global_load_lds_dwordx4 v140, s[86:87]
	s_add_i32 m0, s88, 0x2000
	s_nop 0
	global_load_lds_dwordx4 v142, s[86:87]
	s_mov_b32 m0, s85
	s_nop 0
	global_load_lds_dwordx4 v140, s[30:31]
	s_mov_b32 m0, s33
	s_nop 0
	global_load_lds_dwordx4 v142, s[30:31]
	s_add_u32 s100, s30, 0x80
	s_addc_u32 s101, s31, 0
	s_waitcnt vmcnt(8)
	s_waitcnt lgkmcnt(0)
	s_barrier
	s_waitcnt lgkmcnt(0)
	v_mfma_f32_16x16x32_bf16 v[52:55], v[128:131], v[198:201], v[52:55]
	v_mfma_f32_16x16x32_bf16 v[60:63], v[136:139], v[198:201], v[60:63]
	v_mfma_f32_16x16x32_bf16 v[20:23], v[128:131], v[206:209], v[20:23]
	v_mfma_f32_16x16x32_bf16 v[44:47], v[136:139], v[206:209], v[44:47]
	v_mfma_f32_16x16x32_bf16 v[12:15], v[128:131], v[214:217], v[12:15]
	v_mfma_f32_16x16x32_bf16 v[36:39], v[136:139], v[214:217], v[36:39]
	v_mfma_f32_16x16x32_bf16 v[4:7], v[128:131], v[222:225], v[4:7]
	v_mfma_f32_16x16x32_bf16 v[28:31], v[136:139], v[222:225], v[28:31]
	v_mfma_f32_16x16x32_bf16 v[52:55], v[132:135], v[202:205], v[52:55]
	v_mfma_f32_16x16x32_bf16 v[60:63], v[174:177], v[202:205], v[60:63]
	v_mfma_f32_16x16x32_bf16 v[20:23], v[132:135], v[210:213], v[20:23]
	v_mfma_f32_16x16x32_bf16 v[44:47], v[174:177], v[210:213], v[44:47]
	v_mfma_f32_16x16x32_bf16 v[12:15], v[132:135], v[218:221], v[12:15]
	v_mfma_f32_16x16x32_bf16 v[36:39], v[174:177], v[218:221], v[36:39]
	v_mfma_f32_16x16x32_bf16 v[4:7], v[132:135], v[226:229], v[4:7]
	v_mfma_f32_16x16x32_bf16 v[28:31], v[174:177], v[226:229], v[28:31]
	v_mfma_f32_16x16x32_bf16 v[56:59], v[178:181], v[198:201], v[56:59]
	v_mfma_f32_16x16x32_bf16 v[48:51], v[186:189], v[198:201], v[48:51]
	v_mfma_f32_16x16x32_bf16 v[40:43], v[178:181], v[206:209], v[40:43]
	v_mfma_f32_16x16x32_bf16 v[16:19], v[186:189], v[206:209], v[16:19]
	v_mfma_f32_16x16x32_bf16 v[32:35], v[178:181], v[214:217], v[32:35]
	v_mfma_f32_16x16x32_bf16 v[8:11], v[186:189], v[214:217], v[8:11]
	v_mfma_f32_16x16x32_bf16 v[24:27], v[178:181], v[222:225], v[24:27]
	v_mfma_f32_16x16x32_bf16 v[0:3], v[186:189], v[222:225], v[0:3]
	v_mfma_f32_16x16x32_bf16 v[56:59], v[182:185], v[202:205], v[56:59]
	v_mfma_f32_16x16x32_bf16 v[48:51], v[190:193], v[202:205], v[48:51]
	v_mfma_f32_16x16x32_bf16 v[40:43], v[182:185], v[210:213], v[40:43]
	v_mfma_f32_16x16x32_bf16 v[16:19], v[190:193], v[210:213], v[16:19]
	v_mfma_f32_16x16x32_bf16 v[32:35], v[182:185], v[218:221], v[32:35]
	v_mfma_f32_16x16x32_bf16 v[8:11], v[190:193], v[218:221], v[8:11]
	v_mfma_f32_16x16x32_bf16 v[24:27], v[182:185], v[226:229], v[24:27]
	v_mfma_f32_16x16x32_bf16 v[0:3], v[190:193], v[226:229], v[0:3]
	s_barrier
; #define GP_STAGE(bufoff, gbase, voff) do { _Pragma("unroll") for (int _i = 0; _i < 2; ++_i) \
;         __builtin_amdgcn_global_load_lds((const unsigned*)((const char*)(gbase) + (voff)[_i]), (LAS unsigned*)(lds + (bufoff) + ldsw + _i * 8192), 16, 0, 0); } while (0)
; #define GP_LDA(dst, b, h) do { _Pragma("unroll") for (int m = 0; m < 4; ++m) _Pragma("unroll") for (int k = 0; k < 2; ++k) dst[m][k] = *(const LAS bf16x8*)(lds + GP_SA(b, h) + aoff + m * 2048 + k * 1024); } while (0)
; #define GP_LDB(dst, b, h) do { _Pragma("unroll") for (int n = 0; n < 2; ++n) _Pragma("unroll") for (int k = 0; k < 2; ++k) dst[n][k] = *(const LAS bf16x8*)(lds + GP_SB(b, h) + boff + n * 2048 + k * 1024); } while (0)
; #define GP_WAIT_V(n) asm volatile("s_waitcnt vmcnt(" #n ")" ::: "memory")
; #define GP_BAR __builtin_amdgcn_s_barrier()
; template <class Epi, class Sched>
; __device__ __forceinline__ void gemm_phase(LAS unsigned char* lds, const int lda, const int ldb, const int K, const Sched& S, const Epi& E, const int widx) {
;     ...
;         for (int t = 0; t < nt; t += 2) {
;             const bool last = (t == nt - 2);
;             const char* a1 = cA + (size_t)(t + 1) * kstep;
;             const char* a2 = last ? nA : cA + (size_t)(t + 2) * kstep; const char* b2 = last ? nB : cB + (size_t)(t + 2) * kstep;
;             const char* a3 = a2 + kstep; const char* b3 = b2 + kstep;
;             GP_LDB(B0, 0, 0); GP_LDB(B1, 0, 1); GP_SCHED; GP_LDA(At, 0, 0); GP_STAGE(GP_SA(1, 1), a1 + hstepA, voffA);
;             GP_WAIT_V(8); GP_WAIT_L(0); GP_BAR; GP_MMA(0, 0, At, B0); GP_MMA(0, 1, At, B1); GP_BAR; GP_SCHED;
;             GP_LDA(At, 0, 1); GP_STAGE(GP_SB(0, 0), b2, voffB); GP_STAGE(GP_SB(0, 1), b2 + hstepB, voffB); GP_STAGE(GP_SA(0, 0), a2, voffA);
;             GP_WAIT_V(8); GP_WAIT_L(0); GP_BAR; GP_MMA(1, 0, At, B0); GP_MMA(1, 1, At, B1); GP_BAR; GP_SCHED;
;             GP_LDB(B0, 1, 0); GP_LDB(B1, 1, 1); GP_SCHED; GP_LDA(At, 1, 0); GP_STAGE(GP_SA(0, 1), a2 + hstepA, voffA);
;             GP_WAIT_V(8); GP_WAIT_L(0); GP_BAR; GP_MMA(0, 0, At, B0); GP_MMA(0, 1, At, B1); GP_BAR; GP_SCHED;
;             GP_LDA(At, 1, 1); GP_STAGE(GP_SB(1, 0), b3, voffB); GP_STAGE(GP_SB(1, 1), b3 + hstepB, voffB); GP_STAGE(GP_SA(1, 0), a3, voffA);
;             GP_WAIT_V(8); GP_WAIT_L(0); GP_BAR; GP_MMA(1, 0, At, B0); GP_MMA(1, 1, At, B1); GP_BAR; GP_SCHED;
;         }
;         if (wr == 0) GP_BAR;
	s_add_i32 s86, 0, 0x18000
	v_add_u32_e32 v144, s86, v167
	s_add_i32 s87, 0, 0x1c000
	ds_read_b128 v[128:131], v144
	ds_read_b128 v[132:135], v144 offset:1024
	ds_read_b128 v[136:139], v144 offset:2048
	ds_read_b128 v[174:177], v144 offset:3072
	v_add_u32_e32 v144, s87, v167
	ds_read_b128 v[178:181], v144
	ds_read_b128 v[182:185], v144 offset:1024
	ds_read_b128 v[186:189], v144 offset:2048
	ds_read_b128 v[190:193], v144 offset:3072
	s_add_u32 s30, s30, 0x40000
	s_addc_u32 s31, s31, 0
	s_mov_b32 m0, s74
	ds_read_b128 v[198:201], v196 offset:32768
	ds_read_b128 v[202:205], v196 offset:33792
	ds_read_b128 v[206:209], v196 offset:34816
	ds_read_b128 v[210:213], v196 offset:35840
	ds_read_b128 v[214:217], v196 offset:36864
	ds_read_b128 v[218:221], v196 offset:37888
	ds_read_b128 v[222:225], v196 offset:38912
	ds_read_b128 v[226:229], v196 offset:39936
	global_load_lds_dwordx4 v140, s[30:31]
	s_mov_b32 m0, s75
	s_nop 0
	global_load_lds_dwordx4 v142, s[30:31]
	s_waitcnt vmcnt(8)
	s_waitcnt lgkmcnt(0)
	s_barrier
	s_waitcnt lgkmcnt(0)
	v_mfma_f32_16x16x32_bf16 v[116:119], v[128:131], v[198:201], v[116:119]
	v_mfma_f32_16x16x32_bf16 v[124:127], v[136:139], v[198:201], v[124:127]
	v_mfma_f32_16x16x32_bf16 v[84:87], v[128:131], v[206:209], v[84:87]
	v_mfma_f32_16x16x32_bf16 v[108:111], v[136:139], v[206:209], v[108:111]
	v_mfma_f32_16x16x32_bf16 v[76:79], v[128:131], v[214:217], v[76:79]
	v_mfma_f32_16x16x32_bf16 v[100:103], v[136:139], v[214:217], v[100:103]
	v_mfma_f32_16x16x32_bf16 v[68:71], v[128:131], v[222:225], v[68:71]
	v_mfma_f32_16x16x32_bf16 v[92:95], v[136:139], v[222:225], v[92:95]
	v_mfma_f32_16x16x32_bf16 v[116:119], v[132:135], v[202:205], v[116:119]
	v_mfma_f32_16x16x32_bf16 v[124:127], v[174:177], v[202:205], v[124:127]
	v_mfma_f32_16x16x32_bf16 v[84:87], v[132:135], v[210:213], v[84:87]
	v_mfma_f32_16x16x32_bf16 v[108:111], v[174:177], v[210:213], v[108:111]
	v_mfma_f32_16x16x32_bf16 v[76:79], v[132:135], v[218:221], v[76:79]
	v_mfma_f32_16x16x32_bf16 v[100:103], v[174:177], v[218:221], v[100:103]
	v_mfma_f32_16x16x32_bf16 v[68:71], v[132:135], v[226:229], v[68:71]
	v_mfma_f32_16x16x32_bf16 v[92:95], v[174:177], v[226:229], v[92:95]
	v_mfma_f32_16x16x32_bf16 v[120:123], v[178:181], v[198:201], v[120:123]
	v_mfma_f32_16x16x32_bf16 v[112:115], v[186:189], v[198:201], v[112:115]
	v_mfma_f32_16x16x32_bf16 v[104:107], v[178:181], v[206:209], v[104:107]
	v_mfma_f32_16x16x32_bf16 v[80:83], v[186:189], v[206:209], v[80:83]
	v_mfma_f32_16x16x32_bf16 v[96:99], v[178:181], v[214:217], v[96:99]
	v_mfma_f32_16x16x32_bf16 v[72:75], v[186:189], v[214:217], v[72:75]
	v_mfma_f32_16x16x32_bf16 v[88:91], v[178:181], v[222:225], v[88:91]
	v_mfma_f32_16x16x32_bf16 v[64:67], v[186:189], v[222:225], v[64:67]
	v_mfma_f32_16x16x32_bf16 v[120:123], v[182:185], v[202:205], v[120:123]
	v_mfma_f32_16x16x32_bf16 v[112:115], v[190:193], v[202:205], v[112:115]
	v_mfma_f32_16x16x32_bf16 v[104:107], v[182:185], v[210:213], v[104:107]
	v_mfma_f32_16x16x32_bf16 v[80:83], v[190:193], v[210:213], v[80:83]
	v_mfma_f32_16x16x32_bf16 v[96:99], v[182:185], v[218:221], v[96:99]
	v_mfma_f32_16x16x32_bf16 v[72:75], v[190:193], v[218:221], v[72:75]
	v_mfma_f32_16x16x32_bf16 v[88:91], v[182:185], v[226:229], v[88:91]
	v_mfma_f32_16x16x32_bf16 v[64:67], v[190:193], v[226:229], v[64:67]
	s_barrier
	s_add_u32 s98, s92, 0x80
	s_addc_u32 s99, s93, 0
	s_add_i32 s30, s86, s97
	s_mov_b32 m0, s30
	ds_read_b128 v[198:201], v196 offset:49152
	ds_read_b128 v[202:205], v196 offset:50176
	ds_read_b128 v[206:209], v196 offset:51200
	ds_read_b128 v[210:213], v196 offset:52224
	ds_read_b128 v[214:217], v196 offset:53248
	ds_read_b128 v[218:221], v196 offset:54272
	ds_read_b128 v[222:225], v196 offset:55296
	ds_read_b128 v[226:229], v196 offset:56320
	global_load_lds_dwordx4 v140, s[98:99]
	s_add_i32 m0, s30, 0x2000
	s_add_u32 s30, s92, 0x40080
	s_addc_u32 s31, s93, 0
	s_add_i32 s86, s87, s97
	global_load_lds_dwordx4 v142, s[98:99]
	s_mov_b32 m0, s86
	s_nop 0
	global_load_lds_dwordx4 v140, s[30:31]
	s_add_i32 m0, s86, 0x2000
	s_nop 0
	global_load_lds_dwordx4 v142, s[30:31]
	s_mov_b32 m0, s76
	s_nop 0
	global_load_lds_dwordx4 v140, s[100:101]
	s_mov_b32 m0, s77
	s_nop 0
	global_load_lds_dwordx4 v142, s[100:101]
	s_waitcnt vmcnt(8)
	s_waitcnt lgkmcnt(0)
	s_barrier
	s_waitcnt lgkmcnt(0)
	v_mfma_f32_16x16x32_bf16 v[52:55], v[128:131], v[198:201], v[52:55]
	v_mfma_f32_16x16x32_bf16 v[60:63], v[136:139], v[198:201], v[60:63]
	v_mfma_f32_16x16x32_bf16 v[20:23], v[128:131], v[206:209], v[20:23]
	v_mfma_f32_16x16x32_bf16 v[44:47], v[136:139], v[206:209], v[44:47]
	v_mfma_f32_16x16x32_bf16 v[12:15], v[128:131], v[214:217], v[12:15]
	v_mfma_f32_16x16x32_bf16 v[36:39], v[136:139], v[214:217], v[36:39]
	v_mfma_f32_16x16x32_bf16 v[4:7], v[128:131], v[222:225], v[4:7]
	v_mfma_f32_16x16x32_bf16 v[28:31], v[136:139], v[222:225], v[28:31]
	v_mfma_f32_16x16x32_bf16 v[52:55], v[132:135], v[202:205], v[52:55]
	v_mfma_f32_16x16x32_bf16 v[60:63], v[174:177], v[202:205], v[60:63]
	v_mfma_f32_16x16x32_bf16 v[20:23], v[132:135], v[210:213], v[20:23]
	v_mfma_f32_16x16x32_bf16 v[44:47], v[174:177], v[210:213], v[44:47]
	v_mfma_f32_16x16x32_bf16 v[12:15], v[132:135], v[218:221], v[12:15]
	v_mfma_f32_16x16x32_bf16 v[36:39], v[174:177], v[218:221], v[36:39]
	v_mfma_f32_16x16x32_bf16 v[4:7], v[132:135], v[226:229], v[4:7]
	v_mfma_f32_16x16x32_bf16 v[28:31], v[174:177], v[226:229], v[28:31]
	v_mfma_f32_16x16x32_bf16 v[56:59], v[178:181], v[198:201], v[56:59]
	v_mfma_f32_16x16x32_bf16 v[48:51], v[186:189], v[198:201], v[48:51]
	v_mfma_f32_16x16x32_bf16 v[40:43], v[178:181], v[206:209], v[40:43]
	v_mfma_f32_16x16x32_bf16 v[16:19], v[186:189], v[206:209], v[16:19]
	v_mfma_f32_16x16x32_bf16 v[32:35], v[178:181], v[214:217], v[32:35]
	v_mfma_f32_16x16x32_bf16 v[8:11], v[186:189], v[214:217], v[8:11]
	v_mfma_f32_16x16x32_bf16 v[24:27], v[178:181], v[222:225], v[24:27]
	v_mfma_f32_16x16x32_bf16 v[0:3], v[186:189], v[222:225], v[0:3]
	v_mfma_f32_16x16x32_bf16 v[56:59], v[182:185], v[202:205], v[56:59]
	v_mfma_f32_16x16x32_bf16 v[48:51], v[190:193], v[202:205], v[48:51]
	v_mfma_f32_16x16x32_bf16 v[40:43], v[182:185], v[210:213], v[40:43]
	v_mfma_f32_16x16x32_bf16 v[16:19], v[190:193], v[210:213], v[16:19]
	v_mfma_f32_16x16x32_bf16 v[32:35], v[182:185], v[218:221], v[32:35]
	v_mfma_f32_16x16x32_bf16 v[8:11], v[190:193], v[218:221], v[8:11]
	v_mfma_f32_16x16x32_bf16 v[24:27], v[182:185], v[226:229], v[24:27]
	v_mfma_f32_16x16x32_bf16 v[0:3], v[190:193], v[226:229], v[0:3]
	s_barrier
	s_add_i32 s83, s83, 2
	s_add_u32 s4, s4, 0x100
	s_addc_u32 s5, s5, 0
	s_add_u32 s81, s81, 0x100
	s_addc_u32 s82, s82, 0
	s_cmp_gt_u32 s83, 13
	s_cbranch_scc0 .LBB0_135
	s_and_b64 vcc, exec, s[72:73]
	s_cbranch_vccz .LBB0_139
	s_barrier
	s_cmp_gt_i32 s13, 2
	s_mov_b64 s[4:5], -1
	s_cbranch_scc1 .LBB0_140

; #define GP_STAGE(bufoff, gbase, voff) do { _Pragma("unroll") for (int _i = 0; _i < 2; ++_i) \
;         __builtin_amdgcn_global_load_lds((const unsigned*)((const char*)(gbase) + (voff)[_i]), (LAS unsigned*)(lds + (bufoff) + ldsw + _i * 8192), 16, 0, 0); } while (0)
; #define GP_LDA(dst, b, h) do { _Pragma("unroll") for (int m = 0; m < 4; ++m) _Pragma("unroll") for (int k = 0; k < 2; ++k) dst[m][k] = *(const LAS bf16x8*)(lds + GP_SA(b, h) + aoff + m * 2048 + k * 1024); } while (0)
; #define GP_LDB(dst, b, h) do { _Pragma("unroll") for (int n = 0; n < 2; ++n) _Pragma("unroll") for (int k = 0; k < 2; ++k) dst[n][k] = *(const LAS bf16x8*)(lds + GP_SB(b, h) + boff + n * 2048 + k * 1024); } while (0)
; #define GP_MMA(ai, bj, At, Bt) do { __builtin_amdgcn_s_setprio(1); _Pragma("unroll") for (int m = 0; m < 4; ++m) _Pragma("unroll") for (int n = 0; n < 2; ++n) _Pragma("unroll") for (int k = 0; k < 2; ++k) \
;         acc[ai][bj][m][n] = __builtin_amdgcn_mfma_f32_16x16x32_bf16(Bt[n][k], At[m][k], acc[ai][bj][m][n], 0, 0, 0); __builtin_amdgcn_s_setprio(0); } while (0)
; #define GP_WAIT_V(n) asm volatile("s_waitcnt vmcnt(" #n ")" ::: "memory")
; #define GP_WAIT_L(n) asm volatile("s_waitcnt lgkmcnt(" #n ")" ::: "memory")
; #define GP_BAR __builtin_amdgcn_s_barrier()
; #define GP_SCHED __builtin_amdgcn_sched_barrier(0)
; template <class Epi, class Sched>
; __device__ __forceinline__ void gemm_phase(LAS unsigned char* lds, const int lda, const int ldb, const int K, const Sched& S, const Epi& E, const int widx) {
;     ...
;             GP_LDB(B0, 0, 0); GP_LDB(B1, 0, 1); GP_SCHED; GP_LDA(At, 0, 0); GP_STAGE(GP_SA(1, 1), a1 + hstepA, voffA);
;             GP_WAIT_V(8); GP_WAIT_L(0); GP_BAR; GP_MMA(0, 0, At, B0); GP_MMA(0, 1, At, B1); GP_BAR; GP_SCHED;
;             GP_LDA(At, 0, 1); GP_STAGE(GP_SB(0, 0), b2, voffB); GP_STAGE(GP_SB(0, 1), b2 + hstepB, voffB); GP_STAGE(GP_SA(0, 0), a2, voffA);
;             GP_WAIT_V(8); GP_WAIT_L(0); GP_BAR; GP_MMA(1, 0, At, B0); GP_MMA(1, 1, At, B1); GP_BAR; GP_SCHED;
.LBB0_363:
	s_waitcnt lgkmcnt(0)
	ds_read_b128 v[0:3], v144
	ds_read_b128 v[4:7], v144 offset:1024
	ds_read_b128 v[8:11], v144 offset:2048
	ds_read_b128 v[12:15], v144 offset:3072
	ds_read_b128 v[16:19], v145
	ds_read_b128 v[20:23], v145 offset:1024
	ds_read_b128 v[24:27], v145 offset:2048
	ds_read_b128 v[28:31], v145 offset:3072
	s_add_u32 s88, s74, 0x40080
	s_addc_u32 s89, s75, 0
	s_mov_b32 m0, s42
	v_lshl_add_u64 v[64:65], s[88:89], 0, v[128:129]
	ds_read_b128 v[32:35], v146
	ds_read_b128 v[36:39], v146 offset:1024
	ds_read_b128 v[40:43], v146 offset:2048
	ds_read_b128 v[44:47], v146 offset:3072
	ds_read_b128 v[48:51], v146 offset:4096
	ds_read_b128 v[52:55], v146 offset:5120
	ds_read_b128 v[56:59], v146 offset:6144
	ds_read_b128 v[60:63], v146 offset:7168
	global_load_lds_dwordx4 v[64:65], off
	v_lshl_add_u64 v[64:65], s[88:89], 0, v[130:131]
	s_mov_b32 m0, s43
	s_nop 0
	global_load_lds_dwordx4 v[64:65], off
	s_waitcnt vmcnt(8)
	s_waitcnt lgkmcnt(0)
	s_barrier
	s_waitcnt lgkmcnt(0)
	v_mfma_f32_16x16x32_bf16 v[64:67], v[0:3], v[32:35], 0
	v_mfma_f32_16x16x32_bf16 v[68:71], v[8:11], v[32:35], 0
	v_mfma_f32_16x16x32_bf16 v[72:75], v[0:3], v[40:43], 0
	v_mfma_f32_16x16x32_bf16 v[76:79], v[8:11], v[40:43], 0
	v_mfma_f32_16x16x32_bf16 v[80:83], v[0:3], v[48:51], 0
	v_mfma_f32_16x16x32_bf16 v[84:87], v[8:11], v[48:51], 0
	v_mfma_f32_16x16x32_bf16 v[88:91], v[0:3], v[56:59], 0
	v_mfma_f32_16x16x32_bf16 v[92:95], v[8:11], v[56:59], 0
	v_mfma_f32_16x16x32_bf16 v[64:67], v[4:7], v[36:39], v[64:67]
	v_mfma_f32_16x16x32_bf16 v[68:71], v[12:15], v[36:39], v[68:71]
	v_mfma_f32_16x16x32_bf16 v[72:75], v[4:7], v[44:47], v[72:75]
	v_mfma_f32_16x16x32_bf16 v[76:79], v[12:15], v[44:47], v[76:79]
	v_mfma_f32_16x16x32_bf16 v[80:83], v[4:7], v[52:55], v[80:83]
	v_mfma_f32_16x16x32_bf16 v[84:87], v[12:15], v[52:55], v[84:87]
	v_mfma_f32_16x16x32_bf16 v[88:91], v[4:7], v[60:63], v[88:91]
	v_mfma_f32_16x16x32_bf16 v[92:95], v[12:15], v[60:63], v[92:95]
	v_mfma_f32_16x16x32_bf16 v[96:99], v[16:19], v[32:35], 0
	v_mfma_f32_16x16x32_bf16 v[32:35], v[24:27], v[32:35], 0
	v_mfma_f32_16x16x32_bf16 v[96:99], v[20:23], v[36:39], v[96:99]
	v_mfma_f32_16x16x32_bf16 v[32:35], v[28:31], v[36:39], v[32:35]
	v_mfma_f32_16x16x32_bf16 v[36:39], v[16:19], v[40:43], 0
	v_mfma_f32_16x16x32_bf16 v[40:43], v[24:27], v[40:43], 0
	v_mfma_f32_16x16x32_bf16 v[36:39], v[20:23], v[44:47], v[36:39]
	v_mfma_f32_16x16x32_bf16 v[40:43], v[28:31], v[44:47], v[40:43]
	v_mfma_f32_16x16x32_bf16 v[44:47], v[16:19], v[48:51], 0
	v_mfma_f32_16x16x32_bf16 v[48:51], v[24:27], v[48:51], 0
	v_mfma_f32_16x16x32_bf16 v[44:47], v[20:23], v[52:55], v[44:47]
	v_mfma_f32_16x16x32_bf16 v[48:51], v[28:31], v[52:55], v[48:51]
	v_mfma_f32_16x16x32_bf16 v[52:55], v[16:19], v[56:59], 0
	v_mfma_f32_16x16x32_bf16 v[56:59], v[24:27], v[56:59], 0
	v_mfma_f32_16x16x32_bf16 v[52:55], v[20:23], v[60:63], v[52:55]
	v_mfma_f32_16x16x32_bf16 v[56:59], v[28:31], v[60:63], v[56:59]
	s_barrier
	v_lshl_add_u64 v[134:135], s[76:77], 0, v[128:129]
	s_mov_b32 m0, s78
	v_lshl_add_u64 v[150:151], v[134:135], 0, s[62:63]
	v_lshl_add_u64 v[162:163], s[76:77], 0, v[130:131]
	s_add_u32 s88, s76, 0x40100
	ds_read_b128 v[60:63], v146 offset:16384
	ds_read_b128 v[100:103], v146 offset:17408
	ds_read_b128 v[104:107], v146 offset:18432
	ds_read_b128 v[108:111], v146 offset:19456
	ds_read_b128 v[112:115], v146 offset:20480
	ds_read_b128 v[116:119], v146 offset:21504
	ds_read_b128 v[120:123], v146 offset:22528
	ds_read_b128 v[124:127], v146 offset:23552
	global_load_lds_dwordx4 v[150:151], off
	v_lshl_add_u64 v[150:151], v[162:163], 0, s[62:63]
	s_mov_b32 m0, s79
	s_addc_u32 s89, s77, 0
	global_load_lds_dwordx4 v[150:151], off
	v_lshl_add_u64 v[150:151], s[88:89], 0, v[128:129]
	s_mov_b32 m0, s80
	v_lshl_add_u64 v[218:219], s[74:75], 0, v[128:129]
	global_load_lds_dwordx4 v[150:151], off
	v_lshl_add_u64 v[150:151], s[88:89], 0, v[130:131]
	s_mov_b32 m0, s81
	v_lshl_add_u64 v[220:221], s[74:75], 0, v[130:131]
	global_load_lds_dwordx4 v[150:151], off
	v_lshl_add_u64 v[150:151], v[218:219], 0, s[62:63]
	s_mov_b32 m0, s12
	s_nop 0
	global_load_lds_dwordx4 v[150:151], off
	v_lshl_add_u64 v[150:151], v[220:221], 0, s[62:63]
	s_mov_b32 m0, s13
	s_nop 0
	global_load_lds_dwordx4 v[150:151], off
	s_waitcnt vmcnt(8)
	s_waitcnt lgkmcnt(0)
	s_barrier
	s_waitcnt lgkmcnt(0)
	v_mfma_f32_16x16x32_bf16 v[150:153], v[0:3], v[60:63], 0
	v_mfma_f32_16x16x32_bf16 v[158:161], v[0:3], v[104:107], 0
	v_mfma_f32_16x16x32_bf16 v[170:173], v[0:3], v[112:115], 0
	v_mfma_f32_16x16x32_bf16 v[0:3], v[0:3], v[120:123], 0
	v_mfma_f32_16x16x32_bf16 v[150:153], v[4:7], v[100:103], v[150:153]
	v_mfma_f32_16x16x32_bf16 v[158:161], v[4:7], v[108:111], v[158:161]
	v_mfma_f32_16x16x32_bf16 v[170:173], v[4:7], v[116:119], v[170:173]
	v_mfma_f32_16x16x32_bf16 v[0:3], v[4:7], v[124:127], v[0:3]
	v_mfma_f32_16x16x32_bf16 v[4:7], v[8:11], v[120:123], 0
	v_mfma_f32_16x16x32_bf16 v[154:157], v[8:11], v[60:63], 0
	v_mfma_f32_16x16x32_bf16 v[166:169], v[8:11], v[104:107], 0
	v_mfma_f32_16x16x32_bf16 v[174:177], v[8:11], v[112:115], 0
	v_mfma_f32_16x16x32_bf16 v[4:7], v[12:15], v[124:127], v[4:7]
	v_mfma_f32_16x16x32_bf16 v[154:157], v[12:15], v[100:103], v[154:157]
	v_mfma_f32_16x16x32_bf16 v[166:169], v[12:15], v[108:111], v[166:169]
	v_mfma_f32_16x16x32_bf16 v[174:177], v[12:15], v[116:119], v[174:177]
	v_mfma_f32_16x16x32_bf16 v[8:11], v[16:19], v[60:63], 0
	v_mfma_f32_16x16x32_bf16 v[12:15], v[24:27], v[60:63], 0
	v_mfma_f32_16x16x32_bf16 v[8:11], v[20:23], v[100:103], v[8:11]
	v_mfma_f32_16x16x32_bf16 v[12:15], v[28:31], v[100:103], v[12:15]
	v_mfma_f32_16x16x32_bf16 v[60:63], v[16:19], v[104:107], 0
	v_mfma_f32_16x16x32_bf16 v[100:103], v[24:27], v[104:107], 0
	v_mfma_f32_16x16x32_bf16 v[104:107], v[16:19], v[112:115], 0
	v_mfma_f32_16x16x32_bf16 v[16:19], v[16:19], v[120:123], 0
	v_mfma_f32_16x16x32_bf16 v[60:63], v[20:23], v[108:111], v[60:63]
	v_mfma_f32_16x16x32_bf16 v[100:103], v[28:31], v[108:111], v[100:103]
	v_mfma_f32_16x16x32_bf16 v[104:107], v[20:23], v[116:119], v[104:107]
	v_mfma_f32_16x16x32_bf16 v[108:111], v[24:27], v[112:115], 0
	v_mfma_f32_16x16x32_bf16 v[16:19], v[20:23], v[124:127], v[16:19]
	v_mfma_f32_16x16x32_bf16 v[20:23], v[24:27], v[120:123], 0
	v_mfma_f32_16x16x32_bf16 v[108:111], v[28:31], v[116:119], v[108:111]
	v_mfma_f32_16x16x32_bf16 v[20:23], v[28:31], v[124:127], v[20:23]
	s_barrier
; #define GP_STAGE(bufoff, gbase, voff) do { _Pragma("unroll") for (int _i = 0; _i < 2; ++_i) \
;         __builtin_amdgcn_global_load_lds((const unsigned*)((const char*)(gbase) + (voff)[_i]), (LAS unsigned*)(lds + (bufoff) + ldsw + _i * 8192), 16, 0, 0); } while (0)
; #define GP_LDA(dst, b, h) do { _Pragma("unroll") for (int m = 0; m < 4; ++m) _Pragma("unroll") for (int k = 0; k < 2; ++k) dst[m][k] = *(const LAS bf16x8*)(lds + GP_SA(b, h) + aoff + m * 2048 + k * 1024); } while (0)
; #define GP_LDB(dst, b, h) do { _Pragma("unroll") for (int n = 0; n < 2; ++n) _Pragma("unroll") for (int k = 0; k < 2; ++k) dst[n][k] = *(const LAS bf16x8*)(lds + GP_SB(b, h) + boff + n * 2048 + k * 1024); } while (0)
; #define GP_MMA(ai, bj, At, Bt) do { __builtin_amdgcn_s_setprio(1); _Pragma("unroll") for (int m = 0; m < 4; ++m) _Pragma("unroll") for (int n = 0; n < 2; ++n) _Pragma("unroll") for (int k = 0; k < 2; ++k) \
;         acc[ai][bj][m][n] = __builtin_amdgcn_mfma_f32_16x16x32_bf16(Bt[n][k], At[m][k], acc[ai][bj][m][n], 0, 0, 0); __builtin_amdgcn_s_setprio(0); } while (0)
; #define GP_WAIT_V(n) asm volatile("s_waitcnt vmcnt(" #n ")" ::: "memory")
; #define GP_WAIT_L(n) asm volatile("s_waitcnt lgkmcnt(" #n ")" ::: "memory")
; #define GP_BAR __builtin_amdgcn_s_barrier()
; #define GP_SCHED __builtin_amdgcn_sched_barrier(0)
; template <class Epi, class Sched>
; __device__ __forceinline__ void gemm_phase(LAS unsigned char* lds, const int lda, const int ldb, const int K, const Sched& S, const Epi& E, const int widx) {
;     ...
;             GP_LDB(B0, 1, 0); GP_LDB(B1, 1, 1); GP_SCHED; GP_LDA(At, 1, 0); GP_STAGE(GP_SA(0, 1), a2 + hstepA, voffA);
;             GP_WAIT_V(8); GP_WAIT_L(0); GP_BAR; GP_MMA(0, 0, At, B0); GP_MMA(0, 1, At, B1); GP_BAR; GP_SCHED;
;             GP_LDA(At, 1, 1); GP_STAGE(GP_SB(1, 0), b3, voffB); GP_STAGE(GP_SB(1, 1), b3 + hstepB, voffB); GP_STAGE(GP_SA(1, 0), a3, voffA);
;             GP_WAIT_V(8); GP_WAIT_L(0); GP_BAR; GP_MMA(1, 0, At, B0); GP_MMA(1, 1, At, B1); GP_BAR; GP_SCHED;
	ds_read_b128 v[24:27], v148
	ds_read_b128 v[28:31], v148 offset:1024
	ds_read_b128 v[112:115], v148 offset:2048
	ds_read_b128 v[116:119], v148 offset:3072
	ds_read_b128 v[120:123], v149
	ds_read_b128 v[124:127], v149 offset:1024
	ds_read_b128 v[178:181], v149 offset:2048
	ds_read_b128 v[182:185], v149 offset:3072
	s_add_u32 s88, s74, 0x40100
	s_addc_u32 s89, s75, 0
	s_mov_b32 m0, s33
	v_lshl_add_u64 v[222:223], s[88:89], 0, v[128:129]
	ds_read_b128 v[186:189], v146 offset:32768
	ds_read_b128 v[190:193], v146 offset:33792
	ds_read_b128 v[194:197], v146 offset:34816
	ds_read_b128 v[198:201], v146 offset:35840
	ds_read_b128 v[202:205], v146 offset:36864
	ds_read_b128 v[206:209], v146 offset:37888
	ds_read_b128 v[210:213], v146 offset:38912
	ds_read_b128 v[214:217], v146 offset:39936
	global_load_lds_dwordx4 v[222:223], off
	v_lshl_add_u64 v[222:223], s[88:89], 0, v[130:131]
	s_mov_b32 m0, s34
	s_nop 0
	global_load_lds_dwordx4 v[222:223], off
	s_waitcnt vmcnt(8)
	s_waitcnt lgkmcnt(0)
	s_barrier
	s_waitcnt lgkmcnt(0)
	v_mfma_f32_16x16x32_bf16 v[64:67], v[24:27], v[186:189], v[64:67]
	v_mfma_f32_16x16x32_bf16 v[68:71], v[112:115], v[186:189], v[68:71]
	v_mfma_f32_16x16x32_bf16 v[72:75], v[24:27], v[194:197], v[72:75]
	v_mfma_f32_16x16x32_bf16 v[76:79], v[112:115], v[194:197], v[76:79]
	v_mfma_f32_16x16x32_bf16 v[80:83], v[24:27], v[202:205], v[80:83]
	v_mfma_f32_16x16x32_bf16 v[84:87], v[112:115], v[202:205], v[84:87]
	v_mfma_f32_16x16x32_bf16 v[88:91], v[24:27], v[210:213], v[88:91]
	v_mfma_f32_16x16x32_bf16 v[92:95], v[112:115], v[210:213], v[92:95]
	v_mfma_f32_16x16x32_bf16 v[64:67], v[28:31], v[190:193], v[64:67]
	v_mfma_f32_16x16x32_bf16 v[68:71], v[116:119], v[190:193], v[68:71]
	v_mfma_f32_16x16x32_bf16 v[72:75], v[28:31], v[198:201], v[72:75]
	v_mfma_f32_16x16x32_bf16 v[76:79], v[116:119], v[198:201], v[76:79]
	v_mfma_f32_16x16x32_bf16 v[80:83], v[28:31], v[206:209], v[80:83]
	v_mfma_f32_16x16x32_bf16 v[84:87], v[116:119], v[206:209], v[84:87]
	v_mfma_f32_16x16x32_bf16 v[88:91], v[28:31], v[214:217], v[88:91]
	v_mfma_f32_16x16x32_bf16 v[92:95], v[116:119], v[214:217], v[92:95]
	v_mfma_f32_16x16x32_bf16 v[96:99], v[120:123], v[186:189], v[96:99]
	v_mfma_f32_16x16x32_bf16 v[32:35], v[178:181], v[186:189], v[32:35]
	v_mfma_f32_16x16x32_bf16 v[36:39], v[120:123], v[194:197], v[36:39]
	v_mfma_f32_16x16x32_bf16 v[40:43], v[178:181], v[194:197], v[40:43]
	v_mfma_f32_16x16x32_bf16 v[44:47], v[120:123], v[202:205], v[44:47]
	v_mfma_f32_16x16x32_bf16 v[48:51], v[178:181], v[202:205], v[48:51]
	v_mfma_f32_16x16x32_bf16 v[52:55], v[120:123], v[210:213], v[52:55]
	v_mfma_f32_16x16x32_bf16 v[56:59], v[178:181], v[210:213], v[56:59]
	v_mfma_f32_16x16x32_bf16 v[96:99], v[124:127], v[190:193], v[96:99]
	v_mfma_f32_16x16x32_bf16 v[32:35], v[182:185], v[190:193], v[32:35]
	v_mfma_f32_16x16x32_bf16 v[36:39], v[124:127], v[198:201], v[36:39]
	v_mfma_f32_16x16x32_bf16 v[40:43], v[182:185], v[198:201], v[40:43]
	v_mfma_f32_16x16x32_bf16 v[44:47], v[124:127], v[206:209], v[44:47]
	v_mfma_f32_16x16x32_bf16 v[48:51], v[182:185], v[206:209], v[48:51]
	v_mfma_f32_16x16x32_bf16 v[52:55], v[124:127], v[214:217], v[52:55]
	v_mfma_f32_16x16x32_bf16 v[56:59], v[182:185], v[214:217], v[56:59]
	s_barrier
	s_mov_b32 m0, s82
	v_lshl_add_u64 v[134:135], v[134:135], 0, s[64:65]
	s_add_u32 s76, s76, 0x40180
	ds_read_b128 v[186:189], v146 offset:49152
	ds_read_b128 v[190:193], v146 offset:50176
	ds_read_b128 v[194:197], v146 offset:51200
	ds_read_b128 v[198:201], v146 offset:52224
	ds_read_b128 v[202:205], v146 offset:53248
	ds_read_b128 v[206:209], v146 offset:54272
	ds_read_b128 v[210:213], v146 offset:55296
	ds_read_b128 v[214:217], v146 offset:56320
	global_load_lds_dwordx4 v[134:135], off
	v_lshl_add_u64 v[134:135], v[162:163], 0, s[64:65]
	s_mov_b32 m0, s83
	s_addc_u32 s77, s77, 0
	global_load_lds_dwordx4 v[134:135], off
	v_lshl_add_u64 v[134:135], s[76:77], 0, v[128:129]
	s_mov_b32 m0, s84
	s_nop 0
	global_load_lds_dwordx4 v[134:135], off
	v_lshl_add_u64 v[134:135], s[76:77], 0, v[130:131]
	s_mov_b32 m0, s85
	s_nop 0
	global_load_lds_dwordx4 v[134:135], off
	v_lshl_add_u64 v[134:135], v[218:219], 0, s[64:65]
	s_mov_b32 m0, s35
	s_nop 0
	global_load_lds_dwordx4 v[134:135], off
	v_lshl_add_u64 v[134:135], v[220:221], 0, s[64:65]
	s_mov_b32 m0, s40
	s_nop 0
	global_load_lds_dwordx4 v[134:135], off
	s_waitcnt vmcnt(8)
	s_waitcnt lgkmcnt(0)
	s_barrier
	s_waitcnt lgkmcnt(0)
	v_mfma_f32_16x16x32_bf16 v[0:3], v[24:27], v[210:213], v[0:3]
	v_mfma_f32_16x16x32_bf16 v[4:7], v[112:115], v[210:213], v[4:7]
	v_mfma_f32_16x16x32_bf16 v[150:153], v[24:27], v[186:189], v[150:153]
	v_mfma_f32_16x16x32_bf16 v[154:157], v[112:115], v[186:189], v[154:157]
	v_mfma_f32_16x16x32_bf16 v[158:161], v[24:27], v[194:197], v[158:161]
	v_mfma_f32_16x16x32_bf16 v[166:169], v[112:115], v[194:197], v[166:169]
	v_mfma_f32_16x16x32_bf16 v[170:173], v[24:27], v[202:205], v[170:173]
	v_mfma_f32_16x16x32_bf16 v[174:177], v[112:115], v[202:205], v[174:177]
	v_mfma_f32_16x16x32_bf16 v[0:3], v[28:31], v[214:217], v[0:3]
	v_mfma_f32_16x16x32_bf16 v[4:7], v[116:119], v[214:217], v[4:7]
	v_mfma_f32_16x16x32_bf16 v[150:153], v[28:31], v[190:193], v[150:153]
	v_mfma_f32_16x16x32_bf16 v[154:157], v[116:119], v[190:193], v[154:157]
	v_mfma_f32_16x16x32_bf16 v[158:161], v[28:31], v[198:201], v[158:161]
	v_mfma_f32_16x16x32_bf16 v[166:169], v[116:119], v[198:201], v[166:169]
	v_mfma_f32_16x16x32_bf16 v[170:173], v[28:31], v[206:209], v[170:173]
	v_mfma_f32_16x16x32_bf16 v[174:177], v[116:119], v[206:209], v[174:177]
	v_mfma_f32_16x16x32_bf16 v[8:11], v[120:123], v[186:189], v[8:11]
	v_mfma_f32_16x16x32_bf16 v[12:15], v[178:181], v[186:189], v[12:15]
	v_mfma_f32_16x16x32_bf16 v[24:27], v[120:123], v[194:197], v[60:63]
	v_mfma_f32_16x16x32_bf16 v[28:31], v[178:181], v[194:197], v[100:103]
	v_mfma_f32_16x16x32_bf16 v[60:63], v[120:123], v[202:205], v[104:107]
	v_mfma_f32_16x16x32_bf16 v[100:103], v[178:181], v[202:205], v[108:111]
	v_mfma_f32_16x16x32_bf16 v[16:19], v[120:123], v[210:213], v[16:19]
	v_mfma_f32_16x16x32_bf16 v[20:23], v[178:181], v[210:213], v[20:23]
	v_mfma_f32_16x16x32_bf16 v[8:11], v[124:127], v[190:193], v[8:11]
	v_mfma_f32_16x16x32_bf16 v[12:15], v[182:185], v[190:193], v[12:15]
	v_mfma_f32_16x16x32_bf16 v[24:27], v[124:127], v[198:201], v[24:27]
	v_mfma_f32_16x16x32_bf16 v[28:31], v[182:185], v[198:201], v[28:31]
	v_mfma_f32_16x16x32_bf16 v[60:63], v[124:127], v[206:209], v[60:63]
	v_mfma_f32_16x16x32_bf16 v[100:103], v[182:185], v[206:209], v[100:103]
	v_mfma_f32_16x16x32_bf16 v[16:19], v[124:127], v[214:217], v[16:19]
	v_mfma_f32_16x16x32_bf16 v[20:23], v[182:185], v[214:217], v[20:23]
	s_barrier
; #define GP_STAGE(bufoff, gbase, voff) do { _Pragma("unroll") for (int _i = 0; _i < 2; ++_i) \
;         __builtin_amdgcn_global_load_lds((const unsigned*)((const char*)(gbase) + (voff)[_i]), (LAS unsigned*)(lds + (bufoff) + ldsw + _i * 8192), 16, 0, 0); } while (0)
; #define GP_LDA(dst, b, h) do { _Pragma("unroll") for (int m = 0; m < 4; ++m) _Pragma("unroll") for (int k = 0; k < 2; ++k) dst[m][k] = *(const LAS bf16x8*)(lds + GP_SA(b, h) + aoff + m * 2048 + k * 1024); } while (0)
; #define GP_LDB(dst, b, h) do { _Pragma("unroll") for (int n = 0; n < 2; ++n) _Pragma("unroll") for (int k = 0; k < 2; ++k) dst[n][k] = *(const LAS bf16x8*)(lds + GP_SB(b, h) + boff + n * 2048 + k * 1024); } while (0)
; #define GP_MMA(ai, bj, At, Bt) do { __builtin_amdgcn_s_setprio(1); _Pragma("unroll") for (int m = 0; m < 4; ++m) _Pragma("unroll") for (int n = 0; n < 2; ++n) _Pragma("unroll") for (int k = 0; k < 2; ++k) \
;         acc[ai][bj][m][n] = __builtin_amdgcn_mfma_f32_16x16x32_bf16(Bt[n][k], At[m][k], acc[ai][bj][m][n], 0, 0, 0); __builtin_amdgcn_s_setprio(0); } while (0)
; #define GP_WAIT_V(n) asm volatile("s_waitcnt vmcnt(" #n ")" ::: "memory")
; #define GP_WAIT_L(n) asm volatile("s_waitcnt lgkmcnt(" #n ")" ::: "memory")
; #define GP_BAR __builtin_amdgcn_s_barrier()
; #define GP_SCHED __builtin_amdgcn_sched_barrier(0)
; template <class Epi, class Sched>
; __device__ __forceinline__ void gemm_phase(LAS unsigned char* lds, const int lda, const int ldb, const int K, const Sched& S, const Epi& E, const int widx) {
;     ...
;             GP_LDB(B0, 0, 0); GP_LDB(B1, 0, 1); GP_SCHED; GP_LDA(At, 0, 0); GP_STAGE(GP_SA(1, 1), a1 + hstepA, voffA);
;             GP_WAIT_V(8); GP_WAIT_L(0); GP_BAR; GP_MMA(0, 0, At, B0); GP_MMA(0, 1, At, B1); GP_BAR; GP_SCHED;
;             GP_LDA(At, 0, 1); GP_STAGE(GP_SB(0, 0), b2, voffB); GP_STAGE(GP_SB(0, 1), b2 + hstepB, voffB); GP_STAGE(GP_SA(0, 0), a2, voffA);
;             GP_WAIT_V(8); GP_WAIT_L(0); GP_BAR; GP_MMA(1, 0, At, B0); GP_MMA(1, 1, At, B1); GP_BAR; GP_SCHED;
	ds_read_b128 v[104:107], v144
	ds_read_b128 v[108:111], v144 offset:1024
	ds_read_b128 v[112:115], v144 offset:2048
	ds_read_b128 v[116:119], v144 offset:3072
	ds_read_b128 v[120:123], v145
	ds_read_b128 v[124:127], v145 offset:1024
	ds_read_b128 v[178:181], v145 offset:2048
	ds_read_b128 v[182:185], v145 offset:3072
	s_add_u32 s74, s74, 0x40180
	s_addc_u32 s75, s75, 0
	s_mov_b32 m0, s42
	v_lshl_add_u64 v[134:135], s[74:75], 0, v[128:129]
	ds_read_b128 v[186:189], v146
	ds_read_b128 v[190:193], v146 offset:1024
	ds_read_b128 v[194:197], v146 offset:2048
	ds_read_b128 v[198:201], v146 offset:3072
	ds_read_b128 v[202:205], v146 offset:4096
	ds_read_b128 v[206:209], v146 offset:5120
	ds_read_b128 v[210:213], v146 offset:6144
	ds_read_b128 v[214:217], v146 offset:7168
	global_load_lds_dwordx4 v[134:135], off
	v_lshl_add_u64 v[134:135], s[74:75], 0, v[130:131]
	s_mov_b32 m0, s43
	s_nop 0
	global_load_lds_dwordx4 v[134:135], off
	s_waitcnt vmcnt(8)
	s_waitcnt lgkmcnt(0)
	s_barrier
	s_waitcnt lgkmcnt(0)
	v_mfma_f32_16x16x32_bf16 v[64:67], v[104:107], v[186:189], v[64:67]
	v_mfma_f32_16x16x32_bf16 v[68:71], v[112:115], v[186:189], v[68:71]
	v_mfma_f32_16x16x32_bf16 v[72:75], v[104:107], v[194:197], v[72:75]
	v_mfma_f32_16x16x32_bf16 v[76:79], v[112:115], v[194:197], v[76:79]
	v_mfma_f32_16x16x32_bf16 v[80:83], v[104:107], v[202:205], v[80:83]
	v_mfma_f32_16x16x32_bf16 v[84:87], v[112:115], v[202:205], v[84:87]
	v_mfma_f32_16x16x32_bf16 v[88:91], v[104:107], v[210:213], v[88:91]
	v_mfma_f32_16x16x32_bf16 v[64:67], v[108:111], v[190:193], v[64:67]
	v_mfma_f32_16x16x32_bf16 v[68:71], v[116:119], v[190:193], v[68:71]
	v_mfma_f32_16x16x32_bf16 v[72:75], v[108:111], v[198:201], v[72:75]
	v_mfma_f32_16x16x32_bf16 v[76:79], v[116:119], v[198:201], v[76:79]
	v_mfma_f32_16x16x32_bf16 v[80:83], v[108:111], v[206:209], v[80:83]
	v_mfma_f32_16x16x32_bf16 v[84:87], v[116:119], v[206:209], v[84:87]
	v_mfma_f32_16x16x32_bf16 v[218:221], v[108:111], v[214:217], v[88:91]
	v_mfma_f32_16x16x32_bf16 v[88:91], v[112:115], v[210:213], v[92:95]
	v_mfma_f32_16x16x32_bf16 v[222:225], v[116:119], v[214:217], v[88:91]
	v_mfma_f32_16x16x32_bf16 v[88:91], v[120:123], v[186:189], v[96:99]
	v_mfma_f32_16x16x32_bf16 v[32:35], v[178:181], v[186:189], v[32:35]
	v_mfma_f32_16x16x32_bf16 v[36:39], v[120:123], v[194:197], v[36:39]
	v_mfma_f32_16x16x32_bf16 v[40:43], v[178:181], v[194:197], v[40:43]
	v_mfma_f32_16x16x32_bf16 v[44:47], v[120:123], v[202:205], v[44:47]
	v_mfma_f32_16x16x32_bf16 v[48:51], v[178:181], v[202:205], v[48:51]
	v_mfma_f32_16x16x32_bf16 v[52:55], v[120:123], v[210:213], v[52:55]
	v_mfma_f32_16x16x32_bf16 v[56:59], v[178:181], v[210:213], v[56:59]
	v_mfma_f32_16x16x32_bf16 v[96:99], v[124:127], v[190:193], v[88:91]
	v_mfma_f32_16x16x32_bf16 v[32:35], v[182:185], v[190:193], v[32:35]
	v_mfma_f32_16x16x32_bf16 v[36:39], v[124:127], v[198:201], v[36:39]
	v_mfma_f32_16x16x32_bf16 v[40:43], v[182:185], v[198:201], v[40:43]
	v_mfma_f32_16x16x32_bf16 v[44:47], v[124:127], v[206:209], v[44:47]
	v_mfma_f32_16x16x32_bf16 v[48:51], v[182:185], v[206:209], v[48:51]
	v_mfma_f32_16x16x32_bf16 v[52:55], v[124:127], v[214:217], v[52:55]
	v_mfma_f32_16x16x32_bf16 v[56:59], v[182:185], v[214:217], v[56:59]
	s_barrier
	s_mov_b32 m0, s78
	v_lshl_add_u64 v[134:135], s[70:71], 0, v[128:129]
	s_add_u32 s74, s70, 0x40000
	ds_read_b128 v[88:91], v146 offset:16384
	ds_read_b128 v[92:95], v146 offset:17408
	ds_read_b128 v[186:189], v146 offset:18432
	ds_read_b128 v[190:193], v146 offset:19456
	ds_read_b128 v[194:197], v146 offset:20480
	ds_read_b128 v[198:201], v146 offset:21504
	ds_read_b128 v[202:205], v146 offset:22528
	ds_read_b128 v[206:209], v146 offset:23552
	global_load_lds_dwordx4 v[134:135], off
	v_lshl_add_u64 v[162:163], s[70:71], 0, v[130:131]
	s_mov_b32 m0, s79
	s_addc_u32 s75, s71, 0
	global_load_lds_dwordx4 v[162:163], off
	v_lshl_add_u64 v[210:211], s[74:75], 0, v[128:129]
	s_mov_b32 m0, s80
	v_lshl_add_u64 v[164:165], s[68:69], 0, v[128:129]
	global_load_lds_dwordx4 v[210:211], off
	v_lshl_add_u64 v[210:211], s[74:75], 0, v[130:131]
	s_mov_b32 m0, s81
	v_lshl_add_u64 v[138:139], s[68:69], 0, v[130:131]
	global_load_lds_dwordx4 v[210:211], off
	s_mov_b32 m0, s12
	s_nop 0
	global_load_lds_dwordx4 v[164:165], off
	s_mov_b32 m0, s13
	s_nop 0
	global_load_lds_dwordx4 v[138:139], off
	s_waitcnt vmcnt(8)
	s_waitcnt lgkmcnt(0)
	s_barrier
	s_waitcnt lgkmcnt(0)
	v_mfma_f32_16x16x32_bf16 v[0:3], v[104:107], v[202:205], v[0:3]
	v_mfma_f32_16x16x32_bf16 v[4:7], v[112:115], v[202:205], v[4:7]
	v_mfma_f32_16x16x32_bf16 v[150:153], v[104:107], v[88:91], v[150:153]
	v_mfma_f32_16x16x32_bf16 v[154:157], v[112:115], v[88:91], v[154:157]
	v_mfma_f32_16x16x32_bf16 v[158:161], v[104:107], v[186:189], v[158:161]
	v_mfma_f32_16x16x32_bf16 v[166:169], v[112:115], v[186:189], v[166:169]
	v_mfma_f32_16x16x32_bf16 v[170:173], v[104:107], v[194:197], v[170:173]
	v_mfma_f32_16x16x32_bf16 v[174:177], v[112:115], v[194:197], v[174:177]
	v_mfma_f32_16x16x32_bf16 v[0:3], v[108:111], v[206:209], v[0:3]
	v_mfma_f32_16x16x32_bf16 v[4:7], v[116:119], v[206:209], v[4:7]
	v_mfma_f32_16x16x32_bf16 v[150:153], v[108:111], v[92:95], v[150:153]
	v_mfma_f32_16x16x32_bf16 v[154:157], v[116:119], v[92:95], v[154:157]
	v_mfma_f32_16x16x32_bf16 v[158:161], v[108:111], v[190:193], v[158:161]
	v_mfma_f32_16x16x32_bf16 v[166:169], v[116:119], v[190:193], v[166:169]
	v_mfma_f32_16x16x32_bf16 v[170:173], v[108:111], v[198:201], v[170:173]
	v_mfma_f32_16x16x32_bf16 v[174:177], v[116:119], v[198:201], v[174:177]
	v_mfma_f32_16x16x32_bf16 v[8:11], v[120:123], v[88:91], v[8:11]
	v_mfma_f32_16x16x32_bf16 v[210:213], v[124:127], v[92:95], v[8:11]
	v_mfma_f32_16x16x32_bf16 v[8:11], v[178:181], v[88:91], v[12:15]
	v_mfma_f32_16x16x32_bf16 v[214:217], v[182:185], v[92:95], v[8:11]
	v_mfma_f32_16x16x32_bf16 v[8:11], v[120:123], v[186:189], v[24:27]
	v_mfma_f32_16x16x32_bf16 v[226:229], v[124:127], v[190:193], v[8:11]
	v_mfma_f32_16x16x32_bf16 v[8:11], v[178:181], v[186:189], v[28:31]
	v_mfma_f32_16x16x32_bf16 v[186:189], v[182:185], v[190:193], v[8:11]
	v_mfma_f32_16x16x32_bf16 v[8:11], v[120:123], v[194:197], v[60:63]
	v_mfma_f32_16x16x32_bf16 v[190:193], v[124:127], v[198:201], v[8:11]
	v_mfma_f32_16x16x32_bf16 v[8:11], v[178:181], v[194:197], v[100:103]
	v_mfma_f32_16x16x32_bf16 v[194:197], v[182:185], v[198:201], v[8:11]
	v_mfma_f32_16x16x32_bf16 v[8:11], v[120:123], v[202:205], v[16:19]
	v_mfma_f32_16x16x32_bf16 v[198:201], v[124:127], v[206:209], v[8:11]
	v_mfma_f32_16x16x32_bf16 v[8:11], v[178:181], v[202:205], v[20:23]
	v_mfma_f32_16x16x32_bf16 v[178:181], v[182:185], v[206:209], v[8:11]
	s_barrier
; #define GP_STAGE(bufoff, gbase, voff) do { _Pragma("unroll") for (int _i = 0; _i < 2; ++_i) \
;         __builtin_amdgcn_global_load_lds((const unsigned*)((const char*)(gbase) + (voff)[_i]), (LAS unsigned*)(lds + (bufoff) + ldsw + _i * 8192), 16, 0, 0); } while (0)
; #define GP_LDA(dst, b, h) do { _Pragma("unroll") for (int m = 0; m < 4; ++m) _Pragma("unroll") for (int k = 0; k < 2; ++k) dst[m][k] = *(const LAS bf16x8*)(lds + GP_SA(b, h) + aoff + m * 2048 + k * 1024); } while (0)
; #define GP_LDB(dst, b, h) do { _Pragma("unroll") for (int n = 0; n < 2; ++n) _Pragma("unroll") for (int k = 0; k < 2; ++k) dst[n][k] = *(const LAS bf16x8*)(lds + GP_SB(b, h) + boff + n * 2048 + k * 1024); } while (0)
; #define GP_MMA(ai, bj, At, Bt) do { __builtin_amdgcn_s_setprio(1); _Pragma("unroll") for (int m = 0; m < 4; ++m) _Pragma("unroll") for (int n = 0; n < 2; ++n) _Pragma("unroll") for (int k = 0; k < 2; ++k) \
;         acc[ai][bj][m][n] = __builtin_amdgcn_mfma_f32_16x16x32_bf16(Bt[n][k], At[m][k], acc[ai][bj][m][n], 0, 0, 0); __builtin_amdgcn_s_setprio(0); } while (0)
; #define GP_WAIT_V(n) asm volatile("s_waitcnt vmcnt(" #n ")" ::: "memory")
; #define GP_WAIT_L(n) asm volatile("s_waitcnt lgkmcnt(" #n ")" ::: "memory")
; #define GP_BAR __builtin_amdgcn_s_barrier()
; #define GP_SCHED __builtin_amdgcn_sched_barrier(0)
; template <class Epi, class Sched>
; __device__ __forceinline__ void gemm_phase(LAS unsigned char* lds, const int lda, const int ldb, const int K, const Sched& S, const Epi& E, const int widx) {
;     ...
;             GP_LDB(B0, 1, 0); GP_LDB(B1, 1, 1); GP_SCHED; GP_LDA(At, 1, 0); GP_STAGE(GP_SA(0, 1), a2 + hstepA, voffA);
;             GP_WAIT_V(8); GP_WAIT_L(0); GP_BAR; GP_MMA(0, 0, At, B0); GP_MMA(0, 1, At, B1); GP_BAR; GP_SCHED;
;             GP_LDA(At, 1, 1); GP_STAGE(GP_SB(1, 0), b3, voffB); GP_STAGE(GP_SB(1, 1), b3 + hstepB, voffB); GP_STAGE(GP_SA(1, 0), a3, voffA);
;             GP_WAIT_V(8); GP_WAIT_L(0); GP_BAR; GP_MMA(1, 0, At, B0); GP_MMA(1, 1, At, B1); GP_BAR; GP_SCHED;
;         }
;         if (wr == 0) GP_BAR;
	s_nop 4
	ds_read_b128 v[8:11], v148
	ds_read_b128 v[12:15], v148 offset:1024
	ds_read_b128 v[16:19], v148 offset:2048
	ds_read_b128 v[20:23], v148 offset:3072
	ds_read_b128 v[182:185], v149
	ds_read_b128 v[202:205], v149 offset:1024
	ds_read_b128 v[206:209], v149 offset:2048
	ds_read_b128 v[230:233], v149 offset:3072
	s_add_u32 s74, s68, 0x40000
	s_addc_u32 s75, s69, 0
	s_mov_b32 m0, s33
	v_lshl_add_u64 v[88:89], s[74:75], 0, v[128:129]
	ds_read_b128 v[24:27], v146 offset:32768
	ds_read_b128 v[28:31], v146 offset:33792
	ds_read_b128 v[60:63], v146 offset:34816
	ds_read_b128 v[234:237], v146 offset:35840
	ds_read_b128 v[238:241], v146 offset:36864
	ds_read_b128 v[242:245], v146 offset:37888
	ds_read_b128 v[246:249], v146 offset:38912
	ds_read_b128 v[250:253], v146 offset:39936
	global_load_lds_dwordx4 v[88:89], off
	v_lshl_add_u64 v[88:89], s[74:75], 0, v[130:131]
	s_mov_b32 m0, s34
	s_nop 0
	global_load_lds_dwordx4 v[88:89], off
	s_waitcnt vmcnt(8)
	s_waitcnt lgkmcnt(0)
	s_barrier
	s_waitcnt lgkmcnt(0)
	v_mfma_f32_16x16x32_bf16 v[64:67], v[8:11], v[24:27], v[64:67]
	v_mfma_f32_16x16x32_bf16 v[124:127], v[12:15], v[28:31], v[64:67]
	v_mfma_f32_16x16x32_bf16 v[64:67], v[16:19], v[24:27], v[68:71]
	v_mfma_f32_16x16x32_bf16 v[120:123], v[20:23], v[28:31], v[64:67]
	v_mfma_f32_16x16x32_bf16 v[64:67], v[8:11], v[60:63], v[72:75]
	v_mfma_f32_16x16x32_bf16 v[108:111], v[12:15], v[234:237], v[64:67]
	v_mfma_f32_16x16x32_bf16 v[64:67], v[16:19], v[60:63], v[76:79]
	v_mfma_f32_16x16x32_bf16 v[104:107], v[20:23], v[234:237], v[64:67]
	v_mfma_f32_16x16x32_bf16 v[64:67], v[8:11], v[238:241], v[80:83]
	v_mfma_f32_16x16x32_bf16 v[92:95], v[12:15], v[242:245], v[64:67]
	v_mfma_f32_16x16x32_bf16 v[64:67], v[16:19], v[238:241], v[84:87]
	v_mfma_f32_16x16x32_bf16 v[88:91], v[20:23], v[242:245], v[64:67]
	v_mfma_f32_16x16x32_bf16 v[64:67], v[8:11], v[246:249], v[218:221]
	v_mfma_f32_16x16x32_bf16 v[76:79], v[12:15], v[250:253], v[64:67]
	v_mfma_f32_16x16x32_bf16 v[64:67], v[16:19], v[246:249], v[222:225]
	v_mfma_f32_16x16x32_bf16 v[72:75], v[20:23], v[250:253], v[64:67]
	v_mfma_f32_16x16x32_bf16 v[64:67], v[182:185], v[24:27], v[96:99]
	v_mfma_f32_16x16x32_bf16 v[24:27], v[206:209], v[24:27], v[32:35]
	v_mfma_f32_16x16x32_bf16 v[112:115], v[230:233], v[28:31], v[24:27]
	v_mfma_f32_16x16x32_bf16 v[24:27], v[182:185], v[60:63], v[36:39]
	v_mfma_f32_16x16x32_bf16 v[100:103], v[202:205], v[234:237], v[24:27]
	v_mfma_f32_16x16x32_bf16 v[24:27], v[206:209], v[60:63], v[40:43]
	v_mfma_f32_16x16x32_bf16 v[96:99], v[230:233], v[234:237], v[24:27]
	v_mfma_f32_16x16x32_bf16 v[24:27], v[182:185], v[238:241], v[44:47]
	v_mfma_f32_16x16x32_bf16 v[84:87], v[202:205], v[242:245], v[24:27]
	v_mfma_f32_16x16x32_bf16 v[24:27], v[206:209], v[238:241], v[48:51]
	v_mfma_f32_16x16x32_bf16 v[80:83], v[230:233], v[242:245], v[24:27]
	v_mfma_f32_16x16x32_bf16 v[24:27], v[182:185], v[246:249], v[52:55]
	v_mfma_f32_16x16x32_bf16 v[68:71], v[202:205], v[250:253], v[24:27]
	v_mfma_f32_16x16x32_bf16 v[24:27], v[206:209], v[246:249], v[56:59]
	v_mfma_f32_16x16x32_bf16 v[116:119], v[202:205], v[28:31], v[64:67]
	v_mfma_f32_16x16x32_bf16 v[64:67], v[230:233], v[250:253], v[24:27]
	s_barrier
	s_mov_b32 m0, s82
	s_nop 2
	v_lshl_add_u64 v[24:25], v[134:135], 0, s[60:61]
	s_add_u32 s74, s70, 0x40080
	ds_read_b128 v[32:35], v146 offset:49152
	ds_read_b128 v[36:39], v146 offset:50176
	ds_read_b128 v[218:221], v146 offset:51200
	ds_read_b128 v[222:225], v146 offset:52224
	ds_read_b128 v[234:237], v146 offset:53248
	ds_read_b128 v[238:241], v146 offset:54272
	ds_read_b128 v[242:245], v146 offset:55296
	ds_read_b128 v[246:249], v146 offset:56320
	global_load_lds_dwordx4 v[24:25], off
	v_lshl_add_u64 v[24:25], v[162:163], 0, s[60:61]
	s_mov_b32 m0, s83
	s_addc_u32 s75, s71, 0
	global_load_lds_dwordx4 v[24:25], off
	v_lshl_add_u64 v[24:25], s[74:75], 0, v[128:129]
	s_mov_b32 m0, s84
	s_nop 0
	global_load_lds_dwordx4 v[24:25], off
	v_lshl_add_u64 v[24:25], s[74:75], 0, v[130:131]
	s_mov_b32 m0, s85
	s_nop 0
	global_load_lds_dwordx4 v[24:25], off
	v_lshl_add_u64 v[24:25], v[164:165], 0, s[60:61]
	s_mov_b32 m0, s35
	s_nop 0
	global_load_lds_dwordx4 v[24:25], off
	v_lshl_add_u64 v[24:25], v[138:139], 0, s[60:61]
	s_mov_b32 m0, s40
	s_nop 0
	global_load_lds_dwordx4 v[24:25], off
	s_waitcnt vmcnt(8)
	s_waitcnt lgkmcnt(0)
	s_barrier
	s_waitcnt lgkmcnt(0)
	v_mfma_f32_16x16x32_bf16 v[24:27], v[8:11], v[32:35], v[150:153]
	v_mfma_f32_16x16x32_bf16 v[60:63], v[12:15], v[36:39], v[24:27]
	v_mfma_f32_16x16x32_bf16 v[24:27], v[16:19], v[32:35], v[154:157]
	v_mfma_f32_16x16x32_bf16 v[56:59], v[20:23], v[36:39], v[24:27]
	v_mfma_f32_16x16x32_bf16 v[24:27], v[8:11], v[218:221], v[158:161]
	v_mfma_f32_16x16x32_bf16 v[44:47], v[12:15], v[222:225], v[24:27]
	v_mfma_f32_16x16x32_bf16 v[24:27], v[16:19], v[218:221], v[166:169]
	v_mfma_f32_16x16x32_bf16 v[40:43], v[20:23], v[222:225], v[24:27]
	v_mfma_f32_16x16x32_bf16 v[24:27], v[8:11], v[234:237], v[170:173]
	v_mfma_f32_16x16x32_bf16 v[0:3], v[8:11], v[242:245], v[0:3]
	v_mfma_f32_16x16x32_bf16 v[28:31], v[12:15], v[238:241], v[24:27]
	v_mfma_f32_16x16x32_bf16 v[24:27], v[16:19], v[234:237], v[174:177]
	v_mfma_f32_16x16x32_bf16 v[12:15], v[12:15], v[246:249], v[0:3]
	v_mfma_f32_16x16x32_bf16 v[0:3], v[16:19], v[242:245], v[4:7]
	v_mfma_f32_16x16x32_bf16 v[24:27], v[20:23], v[238:241], v[24:27]
	v_mfma_f32_16x16x32_bf16 v[8:11], v[20:23], v[246:249], v[0:3]
	v_mfma_f32_16x16x32_bf16 v[0:3], v[182:185], v[32:35], v[210:213]
	v_mfma_f32_16x16x32_bf16 v[52:55], v[202:205], v[36:39], v[0:3]
	v_mfma_f32_16x16x32_bf16 v[0:3], v[206:209], v[32:35], v[214:217]
	v_mfma_f32_16x16x32_bf16 v[48:51], v[230:233], v[36:39], v[0:3]
	v_mfma_f32_16x16x32_bf16 v[0:3], v[182:185], v[218:221], v[226:229]
	v_mfma_f32_16x16x32_bf16 v[36:39], v[202:205], v[222:225], v[0:3]
	v_mfma_f32_16x16x32_bf16 v[0:3], v[206:209], v[218:221], v[186:189]
	v_mfma_f32_16x16x32_bf16 v[32:35], v[230:233], v[222:225], v[0:3]
	v_mfma_f32_16x16x32_bf16 v[0:3], v[182:185], v[234:237], v[190:193]
	v_mfma_f32_16x16x32_bf16 v[20:23], v[202:205], v[238:241], v[0:3]
	v_mfma_f32_16x16x32_bf16 v[0:3], v[206:209], v[234:237], v[194:197]
	v_mfma_f32_16x16x32_bf16 v[16:19], v[230:233], v[238:241], v[0:3]
	v_mfma_f32_16x16x32_bf16 v[0:3], v[182:185], v[242:245], v[198:201]
	v_mfma_f32_16x16x32_bf16 v[4:7], v[202:205], v[246:249], v[0:3]
	v_mfma_f32_16x16x32_bf16 v[0:3], v[206:209], v[242:245], v[178:181]
	v_mfma_f32_16x16x32_bf16 v[0:3], v[230:233], v[246:249], v[0:3]
	s_barrier
	s_and_b64 vcc, exec, s[4:5]
	s_cbranch_vccnz .LBB0_365
	s_barrier

; #define GP_STAGE(bufoff, gbase, voff) do { _Pragma("unroll") for (int _i = 0; _i < 2; ++_i) \
;         __builtin_amdgcn_global_load_lds((const unsigned*)((const char*)(gbase) + (voff)[_i]), (LAS unsigned*)(lds + (bufoff) + ldsw + _i * 8192), 16, 0, 0); } while (0)
; #define GP_LDA(dst, b, h) do { _Pragma("unroll") for (int m = 0; m < 4; ++m) _Pragma("unroll") for (int k = 0; k < 2; ++k) dst[m][k] = *(const LAS bf16x8*)(lds + GP_SA(b, h) + aoff + m * 2048 + k * 1024); } while (0)
; #define GP_LDB(dst, b, h) do { _Pragma("unroll") for (int n = 0; n < 2; ++n) _Pragma("unroll") for (int k = 0; k < 2; ++k) dst[n][k] = *(const LAS bf16x8*)(lds + GP_SB(b, h) + boff + n * 2048 + k * 1024); } while (0)
; #define GP_MMA(ai, bj, At, Bt) do { __builtin_amdgcn_s_setprio(1); _Pragma("unroll") for (int m = 0; m < 4; ++m) _Pragma("unroll") for (int n = 0; n < 2; ++n) _Pragma("unroll") for (int k = 0; k < 2; ++k) \
;         acc[ai][bj][m][n] = __builtin_amdgcn_mfma_f32_16x16x32_bf16(Bt[n][k], At[m][k], acc[ai][bj][m][n], 0, 0, 0); __builtin_amdgcn_s_setprio(0); } while (0)
; #define GP_WAIT_V(n) asm volatile("s_waitcnt vmcnt(" #n ")" ::: "memory")
; #define GP_WAIT_L(n) asm volatile("s_waitcnt lgkmcnt(" #n ")" ::: "memory")
; #define GP_BAR __builtin_amdgcn_s_barrier()
; #define GP_SCHED __builtin_amdgcn_sched_barrier(0)
; template <class Epi, class Sched>
; __device__ __forceinline__ void gemm_phase(LAS unsigned char* lds, const int lda, const int ldb, const int K, const Sched& S, const Epi& E, const int widx) {
;     ...
;             GP_LDB(B0, 0, 0); GP_LDB(B1, 0, 1); GP_SCHED; GP_LDA(At, 0, 0); GP_STAGE(GP_SA(1, 1), a1 + hstepA, voffA);
;             GP_WAIT_V(8); GP_WAIT_L(0); GP_BAR; GP_MMA(0, 0, At, B0); GP_MMA(0, 1, At, B1); GP_BAR; GP_SCHED;
;             GP_LDA(At, 0, 1); GP_STAGE(GP_SB(0, 0), b2, voffB); GP_STAGE(GP_SB(0, 1), b2 + hstepB, voffB); GP_STAGE(GP_SA(0, 0), a2, voffA);
;             GP_WAIT_V(8); GP_WAIT_L(0); GP_BAR; GP_MMA(1, 0, At, B0); GP_MMA(1, 1, At, B1); GP_BAR; GP_SCHED;
.LBB0_466:
	ds_read_b128 v[0:3], v154
	ds_read_b128 v[4:7], v154 offset:1024
	ds_read_b128 v[8:11], v154 offset:2048
	ds_read_b128 v[12:15], v154 offset:3072
	ds_read_b128 v[16:19], v155
	ds_read_b128 v[20:23], v155 offset:1024
	ds_read_b128 v[24:27], v155 offset:2048
	ds_read_b128 v[28:31], v155 offset:3072
	s_add_u32 s80, s60, 0x40080
	s_addc_u32 s81, s61, 0
	s_mov_b32 m0, s65
	v_lshl_add_u64 v[64:65], s[80:81], 0, v[134:135]
	ds_read_b128 v[32:35], v156
	ds_read_b128 v[36:39], v156 offset:1024
	ds_read_b128 v[40:43], v156 offset:2048
	ds_read_b128 v[44:47], v156 offset:3072
	ds_read_b128 v[48:51], v156 offset:4096
	ds_read_b128 v[52:55], v156 offset:5120
	ds_read_b128 v[56:59], v156 offset:6144
	ds_read_b128 v[60:63], v156 offset:7168
	global_load_lds_dwordx4 v[64:65], off
	v_lshl_add_u64 v[64:65], s[80:81], 0, v[130:131]
	s_mov_b32 m0, s66
	s_nop 0
	global_load_lds_dwordx4 v[64:65], off
	s_waitcnt vmcnt(8)
	s_waitcnt lgkmcnt(0)
	s_barrier
	s_waitcnt lgkmcnt(0)
	v_mfma_f32_16x16x32_bf16 v[64:67], v[0:3], v[32:35], 0
	v_mfma_f32_16x16x32_bf16 v[68:71], v[8:11], v[32:35], 0
	v_mfma_f32_16x16x32_bf16 v[72:75], v[0:3], v[40:43], 0
	v_mfma_f32_16x16x32_bf16 v[76:79], v[8:11], v[40:43], 0
	v_mfma_f32_16x16x32_bf16 v[80:83], v[0:3], v[48:51], 0
	v_mfma_f32_16x16x32_bf16 v[84:87], v[8:11], v[48:51], 0
	v_mfma_f32_16x16x32_bf16 v[88:91], v[0:3], v[56:59], 0
	v_mfma_f32_16x16x32_bf16 v[92:95], v[8:11], v[56:59], 0
	v_mfma_f32_16x16x32_bf16 v[64:67], v[4:7], v[36:39], v[64:67]
	v_mfma_f32_16x16x32_bf16 v[68:71], v[12:15], v[36:39], v[68:71]
	v_mfma_f32_16x16x32_bf16 v[72:75], v[4:7], v[44:47], v[72:75]
	v_mfma_f32_16x16x32_bf16 v[76:79], v[12:15], v[44:47], v[76:79]
	v_mfma_f32_16x16x32_bf16 v[80:83], v[4:7], v[52:55], v[80:83]
	v_mfma_f32_16x16x32_bf16 v[84:87], v[12:15], v[52:55], v[84:87]
	v_mfma_f32_16x16x32_bf16 v[88:91], v[4:7], v[60:63], v[88:91]
	v_mfma_f32_16x16x32_bf16 v[92:95], v[12:15], v[60:63], v[92:95]
	v_mfma_f32_16x16x32_bf16 v[96:99], v[16:19], v[32:35], 0
	v_mfma_f32_16x16x32_bf16 v[32:35], v[24:27], v[32:35], 0
	v_mfma_f32_16x16x32_bf16 v[96:99], v[20:23], v[36:39], v[96:99]
	v_mfma_f32_16x16x32_bf16 v[32:35], v[28:31], v[36:39], v[32:35]
	v_mfma_f32_16x16x32_bf16 v[36:39], v[16:19], v[40:43], 0
	v_mfma_f32_16x16x32_bf16 v[40:43], v[24:27], v[40:43], 0
	v_mfma_f32_16x16x32_bf16 v[36:39], v[20:23], v[44:47], v[36:39]
	v_mfma_f32_16x16x32_bf16 v[40:43], v[28:31], v[44:47], v[40:43]
	v_mfma_f32_16x16x32_bf16 v[44:47], v[16:19], v[48:51], 0
	v_mfma_f32_16x16x32_bf16 v[48:51], v[24:27], v[48:51], 0
	v_mfma_f32_16x16x32_bf16 v[44:47], v[20:23], v[52:55], v[44:47]
	v_mfma_f32_16x16x32_bf16 v[48:51], v[28:31], v[52:55], v[48:51]
	v_mfma_f32_16x16x32_bf16 v[52:55], v[16:19], v[56:59], 0
	v_mfma_f32_16x16x32_bf16 v[56:59], v[24:27], v[56:59], 0
	v_mfma_f32_16x16x32_bf16 v[52:55], v[20:23], v[60:63], v[52:55]
	v_mfma_f32_16x16x32_bf16 v[56:59], v[28:31], v[60:63], v[56:59]
	s_barrier
	v_lshl_add_u64 v[164:165], s[62:63], 0, v[132:133]
	s_mov_b32 m0, s69
	v_lshl_add_u64 v[136:137], v[164:165], 0, s[48:49]
	v_lshl_add_u64 v[210:211], s[62:63], 0, v[128:129]
	s_add_u32 s80, s62, 0x10100
	ds_read_b128 v[60:63], v156 offset:16384
	ds_read_b128 v[100:103], v156 offset:17408
	ds_read_b128 v[104:107], v156 offset:18432
	ds_read_b128 v[108:111], v156 offset:19456
	ds_read_b128 v[112:115], v156 offset:20480
	ds_read_b128 v[116:119], v156 offset:21504
	ds_read_b128 v[120:123], v156 offset:22528
	ds_read_b128 v[124:127], v156 offset:23552
	global_load_lds_dwordx4 v[136:137], off
	v_lshl_add_u64 v[136:137], v[210:211], 0, s[48:49]
	s_mov_b32 m0, s70
	s_addc_u32 s81, s63, 0
	global_load_lds_dwordx4 v[136:137], off
	v_lshl_add_u64 v[136:137], s[80:81], 0, v[132:133]
	s_mov_b32 m0, s71
	v_lshl_add_u64 v[212:213], s[60:61], 0, v[134:135]
	global_load_lds_dwordx4 v[136:137], off
	v_lshl_add_u64 v[136:137], s[80:81], 0, v[128:129]
	s_mov_b32 m0, s72
	v_lshl_add_u64 v[214:215], s[60:61], 0, v[130:131]
	global_load_lds_dwordx4 v[136:137], off
	v_lshl_add_u64 v[136:137], v[212:213], 0, s[48:49]
	s_mov_b32 m0, s12
	s_nop 0
	global_load_lds_dwordx4 v[136:137], off
	v_lshl_add_u64 v[136:137], v[214:215], 0, s[48:49]
	s_mov_b32 m0, s13
	s_nop 0
	global_load_lds_dwordx4 v[136:137], off
	s_waitcnt vmcnt(8)
	s_waitcnt lgkmcnt(0)
	s_barrier
	s_waitcnt lgkmcnt(0)
	v_mfma_f32_16x16x32_bf16 v[136:139], v[0:3], v[60:63], 0
	v_mfma_f32_16x16x32_bf16 v[144:147], v[0:3], v[104:107], 0
	v_mfma_f32_16x16x32_bf16 v[160:163], v[0:3], v[112:115], 0
	v_mfma_f32_16x16x32_bf16 v[0:3], v[0:3], v[120:123], 0
	v_mfma_f32_16x16x32_bf16 v[136:139], v[4:7], v[100:103], v[136:139]
	v_mfma_f32_16x16x32_bf16 v[144:147], v[4:7], v[108:111], v[144:147]
	v_mfma_f32_16x16x32_bf16 v[160:163], v[4:7], v[116:119], v[160:163]
	v_mfma_f32_16x16x32_bf16 v[0:3], v[4:7], v[124:127], v[0:3]
	v_mfma_f32_16x16x32_bf16 v[4:7], v[8:11], v[120:123], 0
	v_mfma_f32_16x16x32_bf16 v[140:143], v[8:11], v[60:63], 0
	v_mfma_f32_16x16x32_bf16 v[148:151], v[8:11], v[104:107], 0
	v_mfma_f32_16x16x32_bf16 v[166:169], v[8:11], v[112:115], 0
	v_mfma_f32_16x16x32_bf16 v[4:7], v[12:15], v[124:127], v[4:7]
	v_mfma_f32_16x16x32_bf16 v[140:143], v[12:15], v[100:103], v[140:143]
	v_mfma_f32_16x16x32_bf16 v[148:151], v[12:15], v[108:111], v[148:151]
	v_mfma_f32_16x16x32_bf16 v[166:169], v[12:15], v[116:119], v[166:169]
	v_mfma_f32_16x16x32_bf16 v[8:11], v[16:19], v[60:63], 0
	v_mfma_f32_16x16x32_bf16 v[12:15], v[24:27], v[60:63], 0
	v_mfma_f32_16x16x32_bf16 v[8:11], v[20:23], v[100:103], v[8:11]
	v_mfma_f32_16x16x32_bf16 v[12:15], v[28:31], v[100:103], v[12:15]
	v_mfma_f32_16x16x32_bf16 v[60:63], v[16:19], v[104:107], 0
	v_mfma_f32_16x16x32_bf16 v[100:103], v[24:27], v[104:107], 0
	v_mfma_f32_16x16x32_bf16 v[104:107], v[16:19], v[112:115], 0
	v_mfma_f32_16x16x32_bf16 v[16:19], v[16:19], v[120:123], 0
	v_mfma_f32_16x16x32_bf16 v[60:63], v[20:23], v[108:111], v[60:63]
	v_mfma_f32_16x16x32_bf16 v[100:103], v[28:31], v[108:111], v[100:103]
	v_mfma_f32_16x16x32_bf16 v[104:107], v[20:23], v[116:119], v[104:107]
	v_mfma_f32_16x16x32_bf16 v[108:111], v[24:27], v[112:115], 0
	v_mfma_f32_16x16x32_bf16 v[16:19], v[20:23], v[124:127], v[16:19]
	v_mfma_f32_16x16x32_bf16 v[20:23], v[24:27], v[120:123], 0
	v_mfma_f32_16x16x32_bf16 v[108:111], v[28:31], v[116:119], v[108:111]
	v_mfma_f32_16x16x32_bf16 v[20:23], v[28:31], v[124:127], v[20:23]
	s_barrier
; #define GP_STAGE(bufoff, gbase, voff) do { _Pragma("unroll") for (int _i = 0; _i < 2; ++_i) \
;         __builtin_amdgcn_global_load_lds((const unsigned*)((const char*)(gbase) + (voff)[_i]), (LAS unsigned*)(lds + (bufoff) + ldsw + _i * 8192), 16, 0, 0); } while (0)
; #define GP_LDA(dst, b, h) do { _Pragma("unroll") for (int m = 0; m < 4; ++m) _Pragma("unroll") for (int k = 0; k < 2; ++k) dst[m][k] = *(const LAS bf16x8*)(lds + GP_SA(b, h) + aoff + m * 2048 + k * 1024); } while (0)
; #define GP_LDB(dst, b, h) do { _Pragma("unroll") for (int n = 0; n < 2; ++n) _Pragma("unroll") for (int k = 0; k < 2; ++k) dst[n][k] = *(const LAS bf16x8*)(lds + GP_SB(b, h) + boff + n * 2048 + k * 1024); } while (0)
; #define GP_MMA(ai, bj, At, Bt) do { __builtin_amdgcn_s_setprio(1); _Pragma("unroll") for (int m = 0; m < 4; ++m) _Pragma("unroll") for (int n = 0; n < 2; ++n) _Pragma("unroll") for (int k = 0; k < 2; ++k) \
;         acc[ai][bj][m][n] = __builtin_amdgcn_mfma_f32_16x16x32_bf16(Bt[n][k], At[m][k], acc[ai][bj][m][n], 0, 0, 0); __builtin_amdgcn_s_setprio(0); } while (0)
; #define GP_WAIT_V(n) asm volatile("s_waitcnt vmcnt(" #n ")" ::: "memory")
; #define GP_WAIT_L(n) asm volatile("s_waitcnt lgkmcnt(" #n ")" ::: "memory")
; #define GP_BAR __builtin_amdgcn_s_barrier()
; #define GP_SCHED __builtin_amdgcn_sched_barrier(0)
; template <class Epi, class Sched>
; __device__ __forceinline__ void gemm_phase(LAS unsigned char* lds, const int lda, const int ldb, const int K, const Sched& S, const Epi& E, const int widx) {
;     ...
;             GP_LDB(B0, 1, 0); GP_LDB(B1, 1, 1); GP_SCHED; GP_LDA(At, 1, 0); GP_STAGE(GP_SA(0, 1), a2 + hstepA, voffA);
;             GP_WAIT_V(8); GP_WAIT_L(0); GP_BAR; GP_MMA(0, 0, At, B0); GP_MMA(0, 1, At, B1); GP_BAR; GP_SCHED;
;             GP_LDA(At, 1, 1); GP_STAGE(GP_SB(1, 0), b3, voffB); GP_STAGE(GP_SB(1, 1), b3 + hstepB, voffB); GP_STAGE(GP_SA(1, 0), a3, voffA);
;             GP_WAIT_V(8); GP_WAIT_L(0); GP_BAR; GP_MMA(1, 0, At, B0); GP_MMA(1, 1, At, B1); GP_BAR; GP_SCHED;
	ds_read_b128 v[24:27], v157
	ds_read_b128 v[28:31], v157 offset:1024
	ds_read_b128 v[112:115], v157 offset:2048
	ds_read_b128 v[116:119], v157 offset:3072
	ds_read_b128 v[120:123], v158
	ds_read_b128 v[124:127], v158 offset:1024
	ds_read_b128 v[170:173], v158 offset:2048
	ds_read_b128 v[174:177], v158 offset:3072
	s_add_u32 s80, s60, 0x40100
	s_addc_u32 s81, s61, 0
	s_mov_b32 m0, s33
	v_lshl_add_u64 v[216:217], s[80:81], 0, v[134:135]
	ds_read_b128 v[178:181], v156 offset:32768
	ds_read_b128 v[182:185], v156 offset:33792
	ds_read_b128 v[186:189], v156 offset:34816
	ds_read_b128 v[190:193], v156 offset:35840
	ds_read_b128 v[194:197], v156 offset:36864
	ds_read_b128 v[198:201], v156 offset:37888
	ds_read_b128 v[202:205], v156 offset:38912
	ds_read_b128 v[206:209], v156 offset:39936
	global_load_lds_dwordx4 v[216:217], off
	v_lshl_add_u64 v[216:217], s[80:81], 0, v[130:131]
	s_mov_b32 m0, s34
	s_nop 0
	global_load_lds_dwordx4 v[216:217], off
	s_waitcnt vmcnt(8)
	s_waitcnt lgkmcnt(0)
	s_barrier
	s_waitcnt lgkmcnt(0)
	v_mfma_f32_16x16x32_bf16 v[64:67], v[24:27], v[178:181], v[64:67]
	v_mfma_f32_16x16x32_bf16 v[68:71], v[112:115], v[178:181], v[68:71]
	v_mfma_f32_16x16x32_bf16 v[72:75], v[24:27], v[186:189], v[72:75]
	v_mfma_f32_16x16x32_bf16 v[76:79], v[112:115], v[186:189], v[76:79]
	v_mfma_f32_16x16x32_bf16 v[80:83], v[24:27], v[194:197], v[80:83]
	v_mfma_f32_16x16x32_bf16 v[84:87], v[112:115], v[194:197], v[84:87]
	v_mfma_f32_16x16x32_bf16 v[88:91], v[24:27], v[202:205], v[88:91]
	v_mfma_f32_16x16x32_bf16 v[92:95], v[112:115], v[202:205], v[92:95]
	v_mfma_f32_16x16x32_bf16 v[64:67], v[28:31], v[182:185], v[64:67]
	v_mfma_f32_16x16x32_bf16 v[68:71], v[116:119], v[182:185], v[68:71]
	v_mfma_f32_16x16x32_bf16 v[72:75], v[28:31], v[190:193], v[72:75]
	v_mfma_f32_16x16x32_bf16 v[76:79], v[116:119], v[190:193], v[76:79]
	v_mfma_f32_16x16x32_bf16 v[80:83], v[28:31], v[198:201], v[80:83]
	v_mfma_f32_16x16x32_bf16 v[84:87], v[116:119], v[198:201], v[84:87]
	v_mfma_f32_16x16x32_bf16 v[88:91], v[28:31], v[206:209], v[88:91]
	v_mfma_f32_16x16x32_bf16 v[92:95], v[116:119], v[206:209], v[92:95]
	v_mfma_f32_16x16x32_bf16 v[96:99], v[120:123], v[178:181], v[96:99]
	v_mfma_f32_16x16x32_bf16 v[32:35], v[170:173], v[178:181], v[32:35]
	v_mfma_f32_16x16x32_bf16 v[36:39], v[120:123], v[186:189], v[36:39]
	v_mfma_f32_16x16x32_bf16 v[40:43], v[170:173], v[186:189], v[40:43]
	v_mfma_f32_16x16x32_bf16 v[44:47], v[120:123], v[194:197], v[44:47]
	v_mfma_f32_16x16x32_bf16 v[48:51], v[170:173], v[194:197], v[48:51]
	v_mfma_f32_16x16x32_bf16 v[52:55], v[120:123], v[202:205], v[52:55]
	v_mfma_f32_16x16x32_bf16 v[56:59], v[170:173], v[202:205], v[56:59]
	v_mfma_f32_16x16x32_bf16 v[96:99], v[124:127], v[182:185], v[96:99]
	v_mfma_f32_16x16x32_bf16 v[32:35], v[174:177], v[182:185], v[32:35]
	v_mfma_f32_16x16x32_bf16 v[36:39], v[124:127], v[190:193], v[36:39]
	v_mfma_f32_16x16x32_bf16 v[40:43], v[174:177], v[190:193], v[40:43]
	v_mfma_f32_16x16x32_bf16 v[44:47], v[124:127], v[198:201], v[44:47]
	v_mfma_f32_16x16x32_bf16 v[48:51], v[174:177], v[198:201], v[48:51]
	v_mfma_f32_16x16x32_bf16 v[52:55], v[124:127], v[206:209], v[52:55]
	v_mfma_f32_16x16x32_bf16 v[56:59], v[174:177], v[206:209], v[56:59]
	s_barrier
	s_mov_b32 m0, s73
	v_lshl_add_u64 v[164:165], v[164:165], 0, s[50:51]
	s_add_u32 s62, s62, 0x10180
	ds_read_b128 v[178:181], v156 offset:49152
	ds_read_b128 v[182:185], v156 offset:50176
	ds_read_b128 v[186:189], v156 offset:51200
	ds_read_b128 v[190:193], v156 offset:52224
	ds_read_b128 v[194:197], v156 offset:53248
	ds_read_b128 v[198:201], v156 offset:54272
	ds_read_b128 v[202:205], v156 offset:55296
	ds_read_b128 v[206:209], v156 offset:56320
	global_load_lds_dwordx4 v[164:165], off
	v_lshl_add_u64 v[164:165], v[210:211], 0, s[50:51]
	s_mov_b32 m0, s74
	s_addc_u32 s63, s63, 0
	global_load_lds_dwordx4 v[164:165], off
	v_lshl_add_u64 v[164:165], s[62:63], 0, v[132:133]
	s_mov_b32 m0, s75
	s_nop 0
	global_load_lds_dwordx4 v[164:165], off
	v_lshl_add_u64 v[164:165], s[62:63], 0, v[128:129]
	s_mov_b32 m0, s76
	s_nop 0
	global_load_lds_dwordx4 v[164:165], off
	v_lshl_add_u64 v[164:165], v[212:213], 0, s[50:51]
	s_mov_b32 m0, s41
	s_nop 0
	global_load_lds_dwordx4 v[164:165], off
	v_lshl_add_u64 v[164:165], v[214:215], 0, s[50:51]
	s_mov_b32 m0, s42
	s_nop 0
	global_load_lds_dwordx4 v[164:165], off
	s_waitcnt vmcnt(8)
	s_waitcnt lgkmcnt(0)
	s_barrier
	s_waitcnt lgkmcnt(0)
	v_mfma_f32_16x16x32_bf16 v[0:3], v[24:27], v[202:205], v[0:3]
	v_mfma_f32_16x16x32_bf16 v[4:7], v[112:115], v[202:205], v[4:7]
	v_mfma_f32_16x16x32_bf16 v[136:139], v[24:27], v[178:181], v[136:139]
	v_mfma_f32_16x16x32_bf16 v[140:143], v[112:115], v[178:181], v[140:143]
	v_mfma_f32_16x16x32_bf16 v[144:147], v[24:27], v[186:189], v[144:147]
	v_mfma_f32_16x16x32_bf16 v[148:151], v[112:115], v[186:189], v[148:151]
	v_mfma_f32_16x16x32_bf16 v[160:163], v[24:27], v[194:197], v[160:163]
	v_mfma_f32_16x16x32_bf16 v[166:169], v[112:115], v[194:197], v[166:169]
	v_mfma_f32_16x16x32_bf16 v[0:3], v[28:31], v[206:209], v[0:3]
	v_mfma_f32_16x16x32_bf16 v[4:7], v[116:119], v[206:209], v[4:7]
	v_mfma_f32_16x16x32_bf16 v[136:139], v[28:31], v[182:185], v[136:139]
	v_mfma_f32_16x16x32_bf16 v[140:143], v[116:119], v[182:185], v[140:143]
	v_mfma_f32_16x16x32_bf16 v[144:147], v[28:31], v[190:193], v[144:147]
	v_mfma_f32_16x16x32_bf16 v[148:151], v[116:119], v[190:193], v[148:151]
	v_mfma_f32_16x16x32_bf16 v[160:163], v[28:31], v[198:201], v[160:163]
	v_mfma_f32_16x16x32_bf16 v[166:169], v[116:119], v[198:201], v[166:169]
	v_mfma_f32_16x16x32_bf16 v[8:11], v[120:123], v[178:181], v[8:11]
	v_mfma_f32_16x16x32_bf16 v[12:15], v[170:173], v[178:181], v[12:15]
	v_mfma_f32_16x16x32_bf16 v[24:27], v[120:123], v[186:189], v[60:63]
	v_mfma_f32_16x16x32_bf16 v[28:31], v[170:173], v[186:189], v[100:103]
	v_mfma_f32_16x16x32_bf16 v[60:63], v[120:123], v[194:197], v[104:107]
	v_mfma_f32_16x16x32_bf16 v[100:103], v[170:173], v[194:197], v[108:111]
	v_mfma_f32_16x16x32_bf16 v[16:19], v[120:123], v[202:205], v[16:19]
	v_mfma_f32_16x16x32_bf16 v[20:23], v[170:173], v[202:205], v[20:23]
	v_mfma_f32_16x16x32_bf16 v[8:11], v[124:127], v[182:185], v[8:11]
	v_mfma_f32_16x16x32_bf16 v[12:15], v[174:177], v[182:185], v[12:15]
	v_mfma_f32_16x16x32_bf16 v[24:27], v[124:127], v[190:193], v[24:27]
	v_mfma_f32_16x16x32_bf16 v[28:31], v[174:177], v[190:193], v[28:31]
	v_mfma_f32_16x16x32_bf16 v[60:63], v[124:127], v[198:201], v[60:63]
	v_mfma_f32_16x16x32_bf16 v[100:103], v[174:177], v[198:201], v[100:103]
	v_mfma_f32_16x16x32_bf16 v[16:19], v[124:127], v[206:209], v[16:19]
	v_mfma_f32_16x16x32_bf16 v[20:23], v[174:177], v[206:209], v[20:23]
	s_barrier
; #define GP_STAGE(bufoff, gbase, voff) do { _Pragma("unroll") for (int _i = 0; _i < 2; ++_i) \
;         __builtin_amdgcn_global_load_lds((const unsigned*)((const char*)(gbase) + (voff)[_i]), (LAS unsigned*)(lds + (bufoff) + ldsw + _i * 8192), 16, 0, 0); } while (0)
; #define GP_LDA(dst, b, h) do { _Pragma("unroll") for (int m = 0; m < 4; ++m) _Pragma("unroll") for (int k = 0; k < 2; ++k) dst[m][k] = *(const LAS bf16x8*)(lds + GP_SA(b, h) + aoff + m * 2048 + k * 1024); } while (0)
; #define GP_LDB(dst, b, h) do { _Pragma("unroll") for (int n = 0; n < 2; ++n) _Pragma("unroll") for (int k = 0; k < 2; ++k) dst[n][k] = *(const LAS bf16x8*)(lds + GP_SB(b, h) + boff + n * 2048 + k * 1024); } while (0)
; #define GP_MMA(ai, bj, At, Bt) do { __builtin_amdgcn_s_setprio(1); _Pragma("unroll") for (int m = 0; m < 4; ++m) _Pragma("unroll") for (int n = 0; n < 2; ++n) _Pragma("unroll") for (int k = 0; k < 2; ++k) \
;         acc[ai][bj][m][n] = __builtin_amdgcn_mfma_f32_16x16x32_bf16(Bt[n][k], At[m][k], acc[ai][bj][m][n], 0, 0, 0); __builtin_amdgcn_s_setprio(0); } while (0)
; #define GP_WAIT_V(n) asm volatile("s_waitcnt vmcnt(" #n ")" ::: "memory")
; #define GP_WAIT_L(n) asm volatile("s_waitcnt lgkmcnt(" #n ")" ::: "memory")
; #define GP_BAR __builtin_amdgcn_s_barrier()
; #define GP_SCHED __builtin_amdgcn_sched_barrier(0)
; template <class Epi, class Sched>
; __device__ __forceinline__ void gemm_phase(LAS unsigned char* lds, const int lda, const int ldb, const int K, const Sched& S, const Epi& E, const int widx) {
;     ...
;             GP_LDB(B0, 0, 0); GP_LDB(B1, 0, 1); GP_SCHED; GP_LDA(At, 0, 0); GP_STAGE(GP_SA(1, 1), a1 + hstepA, voffA);
;             GP_WAIT_V(8); GP_WAIT_L(0); GP_BAR; GP_MMA(0, 0, At, B0); GP_MMA(0, 1, At, B1); GP_BAR; GP_SCHED;
;             GP_LDA(At, 0, 1); GP_STAGE(GP_SB(0, 0), b2, voffB); GP_STAGE(GP_SB(0, 1), b2 + hstepB, voffB); GP_STAGE(GP_SA(0, 0), a2, voffA);
;             GP_WAIT_V(8); GP_WAIT_L(0); GP_BAR; GP_MMA(1, 0, At, B0); GP_MMA(1, 1, At, B1); GP_BAR; GP_SCHED;
	ds_read_b128 v[104:107], v154
	ds_read_b128 v[108:111], v154 offset:1024
	ds_read_b128 v[112:115], v154 offset:2048
	ds_read_b128 v[116:119], v154 offset:3072
	ds_read_b128 v[120:123], v155
	ds_read_b128 v[124:127], v155 offset:1024
	ds_read_b128 v[170:173], v155 offset:2048
	ds_read_b128 v[174:177], v155 offset:3072
	s_add_u32 s60, s60, 0x40180
	s_addc_u32 s61, s61, 0
	s_mov_b32 m0, s65
	v_lshl_add_u64 v[164:165], s[60:61], 0, v[134:135]
	ds_read_b128 v[178:181], v156
	ds_read_b128 v[182:185], v156 offset:1024
	ds_read_b128 v[186:189], v156 offset:2048
	ds_read_b128 v[190:193], v156 offset:3072
	ds_read_b128 v[194:197], v156 offset:4096
	ds_read_b128 v[198:201], v156 offset:5120
	ds_read_b128 v[202:205], v156 offset:6144
	ds_read_b128 v[206:209], v156 offset:7168
	global_load_lds_dwordx4 v[164:165], off
	v_lshl_add_u64 v[164:165], s[60:61], 0, v[130:131]
	s_mov_b32 m0, s66
	s_nop 0
	global_load_lds_dwordx4 v[164:165], off
	s_waitcnt vmcnt(8)
	s_waitcnt lgkmcnt(0)
	s_barrier
	s_waitcnt lgkmcnt(0)
	v_mfma_f32_16x16x32_bf16 v[64:67], v[104:107], v[178:181], v[64:67]
	v_mfma_f32_16x16x32_bf16 v[68:71], v[112:115], v[178:181], v[68:71]
	v_mfma_f32_16x16x32_bf16 v[72:75], v[104:107], v[186:189], v[72:75]
	v_mfma_f32_16x16x32_bf16 v[76:79], v[112:115], v[186:189], v[76:79]
	v_mfma_f32_16x16x32_bf16 v[80:83], v[104:107], v[194:197], v[80:83]
	v_mfma_f32_16x16x32_bf16 v[84:87], v[112:115], v[194:197], v[84:87]
	v_mfma_f32_16x16x32_bf16 v[88:91], v[104:107], v[202:205], v[88:91]
	v_mfma_f32_16x16x32_bf16 v[64:67], v[108:111], v[182:185], v[64:67]
	v_mfma_f32_16x16x32_bf16 v[68:71], v[116:119], v[182:185], v[68:71]
	v_mfma_f32_16x16x32_bf16 v[72:75], v[108:111], v[190:193], v[72:75]
	v_mfma_f32_16x16x32_bf16 v[76:79], v[116:119], v[190:193], v[76:79]
	v_mfma_f32_16x16x32_bf16 v[80:83], v[108:111], v[198:201], v[80:83]
	v_mfma_f32_16x16x32_bf16 v[84:87], v[116:119], v[198:201], v[84:87]
	v_mfma_f32_16x16x32_bf16 v[210:213], v[108:111], v[206:209], v[88:91]
	v_mfma_f32_16x16x32_bf16 v[88:91], v[112:115], v[202:205], v[92:95]
	v_mfma_f32_16x16x32_bf16 v[214:217], v[116:119], v[206:209], v[88:91]
	v_mfma_f32_16x16x32_bf16 v[88:91], v[120:123], v[178:181], v[96:99]
	v_mfma_f32_16x16x32_bf16 v[32:35], v[170:173], v[178:181], v[32:35]
	v_mfma_f32_16x16x32_bf16 v[36:39], v[120:123], v[186:189], v[36:39]
	v_mfma_f32_16x16x32_bf16 v[40:43], v[170:173], v[186:189], v[40:43]
	v_mfma_f32_16x16x32_bf16 v[44:47], v[120:123], v[194:197], v[44:47]
	v_mfma_f32_16x16x32_bf16 v[48:51], v[170:173], v[194:197], v[48:51]
	v_mfma_f32_16x16x32_bf16 v[52:55], v[120:123], v[202:205], v[52:55]
	v_mfma_f32_16x16x32_bf16 v[56:59], v[170:173], v[202:205], v[56:59]
	v_mfma_f32_16x16x32_bf16 v[96:99], v[124:127], v[182:185], v[88:91]
	v_mfma_f32_16x16x32_bf16 v[32:35], v[174:177], v[182:185], v[32:35]
	v_mfma_f32_16x16x32_bf16 v[36:39], v[124:127], v[190:193], v[36:39]
	v_mfma_f32_16x16x32_bf16 v[40:43], v[174:177], v[190:193], v[40:43]
	v_mfma_f32_16x16x32_bf16 v[44:47], v[124:127], v[198:201], v[44:47]
	v_mfma_f32_16x16x32_bf16 v[48:51], v[174:177], v[198:201], v[48:51]
	v_mfma_f32_16x16x32_bf16 v[52:55], v[124:127], v[206:209], v[52:55]
	v_mfma_f32_16x16x32_bf16 v[56:59], v[174:177], v[206:209], v[56:59]
	s_barrier
	s_mov_b32 m0, s69
	v_lshl_add_u64 v[164:165], s[56:57], 0, v[132:133]
	s_add_u32 s60, s56, 0x10000
	ds_read_b128 v[88:91], v156 offset:16384
	ds_read_b128 v[92:95], v156 offset:17408
	ds_read_b128 v[178:181], v156 offset:18432
	ds_read_b128 v[182:185], v156 offset:19456
	ds_read_b128 v[186:189], v156 offset:20480
	ds_read_b128 v[190:193], v156 offset:21504
	ds_read_b128 v[194:197], v156 offset:22528
	ds_read_b128 v[198:201], v156 offset:23552
	global_load_lds_dwordx4 v[164:165], off
	v_lshl_add_u64 v[246:247], s[56:57], 0, v[128:129]
	s_mov_b32 m0, s70
	s_addc_u32 s61, s57, 0
	global_load_lds_dwordx4 v[246:247], off
	v_lshl_add_u64 v[202:203], s[60:61], 0, v[132:133]
	s_mov_b32 m0, s71
	v_lshl_add_u64 v[248:249], s[54:55], 0, v[134:135]
	global_load_lds_dwordx4 v[202:203], off
	v_lshl_add_u64 v[202:203], s[60:61], 0, v[128:129]
	s_mov_b32 m0, s72
	v_lshl_add_u64 v[250:251], s[54:55], 0, v[130:131]
	global_load_lds_dwordx4 v[202:203], off
	s_mov_b32 m0, s12
	s_nop 0
	global_load_lds_dwordx4 v[248:249], off
	s_mov_b32 m0, s13
	s_nop 0
	global_load_lds_dwordx4 v[250:251], off
	s_waitcnt vmcnt(8)
	s_waitcnt lgkmcnt(0)
	s_barrier
	s_waitcnt lgkmcnt(0)
	v_mfma_f32_16x16x32_bf16 v[0:3], v[104:107], v[194:197], v[0:3]
	v_mfma_f32_16x16x32_bf16 v[4:7], v[112:115], v[194:197], v[4:7]
	v_mfma_f32_16x16x32_bf16 v[136:139], v[104:107], v[88:91], v[136:139]
	v_mfma_f32_16x16x32_bf16 v[140:143], v[112:115], v[88:91], v[140:143]
	v_mfma_f32_16x16x32_bf16 v[144:147], v[104:107], v[178:181], v[144:147]
	v_mfma_f32_16x16x32_bf16 v[148:151], v[112:115], v[178:181], v[148:151]
	v_mfma_f32_16x16x32_bf16 v[160:163], v[104:107], v[186:189], v[160:163]
	v_mfma_f32_16x16x32_bf16 v[166:169], v[112:115], v[186:189], v[166:169]
	v_mfma_f32_16x16x32_bf16 v[0:3], v[108:111], v[198:201], v[0:3]
	v_mfma_f32_16x16x32_bf16 v[4:7], v[116:119], v[198:201], v[4:7]
	v_mfma_f32_16x16x32_bf16 v[136:139], v[108:111], v[92:95], v[136:139]
	v_mfma_f32_16x16x32_bf16 v[140:143], v[116:119], v[92:95], v[140:143]
	v_mfma_f32_16x16x32_bf16 v[144:147], v[108:111], v[182:185], v[144:147]
	v_mfma_f32_16x16x32_bf16 v[148:151], v[116:119], v[182:185], v[148:151]
	v_mfma_f32_16x16x32_bf16 v[160:163], v[108:111], v[190:193], v[160:163]
	v_mfma_f32_16x16x32_bf16 v[166:169], v[116:119], v[190:193], v[166:169]
	v_mfma_f32_16x16x32_bf16 v[8:11], v[120:123], v[88:91], v[8:11]
	v_mfma_f32_16x16x32_bf16 v[202:205], v[124:127], v[92:95], v[8:11]
	v_mfma_f32_16x16x32_bf16 v[8:11], v[170:173], v[88:91], v[12:15]
	v_mfma_f32_16x16x32_bf16 v[206:209], v[174:177], v[92:95], v[8:11]
	v_mfma_f32_16x16x32_bf16 v[8:11], v[120:123], v[178:181], v[24:27]
	v_mfma_f32_16x16x32_bf16 v[218:221], v[124:127], v[182:185], v[8:11]
	v_mfma_f32_16x16x32_bf16 v[8:11], v[170:173], v[178:181], v[28:31]
	v_mfma_f32_16x16x32_bf16 v[178:181], v[174:177], v[182:185], v[8:11]
	v_mfma_f32_16x16x32_bf16 v[8:11], v[120:123], v[186:189], v[60:63]
	v_mfma_f32_16x16x32_bf16 v[182:185], v[124:127], v[190:193], v[8:11]
	v_mfma_f32_16x16x32_bf16 v[8:11], v[170:173], v[186:189], v[100:103]
	v_mfma_f32_16x16x32_bf16 v[186:189], v[174:177], v[190:193], v[8:11]
	v_mfma_f32_16x16x32_bf16 v[8:11], v[120:123], v[194:197], v[16:19]
	v_mfma_f32_16x16x32_bf16 v[190:193], v[124:127], v[198:201], v[8:11]
	v_mfma_f32_16x16x32_bf16 v[8:11], v[170:173], v[194:197], v[20:23]
	v_mfma_f32_16x16x32_bf16 v[170:173], v[174:177], v[198:201], v[8:11]
	s_barrier
; #define GP_STAGE(bufoff, gbase, voff) do { _Pragma("unroll") for (int _i = 0; _i < 2; ++_i) \
;         __builtin_amdgcn_global_load_lds((const unsigned*)((const char*)(gbase) + (voff)[_i]), (LAS unsigned*)(lds + (bufoff) + ldsw + _i * 8192), 16, 0, 0); } while (0)
; #define GP_LDA(dst, b, h) do { _Pragma("unroll") for (int m = 0; m < 4; ++m) _Pragma("unroll") for (int k = 0; k < 2; ++k) dst[m][k] = *(const LAS bf16x8*)(lds + GP_SA(b, h) + aoff + m * 2048 + k * 1024); } while (0)
; #define GP_LDB(dst, b, h) do { _Pragma("unroll") for (int n = 0; n < 2; ++n) _Pragma("unroll") for (int k = 0; k < 2; ++k) dst[n][k] = *(const LAS bf16x8*)(lds + GP_SB(b, h) + boff + n * 2048 + k * 1024); } while (0)
; #define GP_MMA(ai, bj, At, Bt) do { __builtin_amdgcn_s_setprio(1); _Pragma("unroll") for (int m = 0; m < 4; ++m) _Pragma("unroll") for (int n = 0; n < 2; ++n) _Pragma("unroll") for (int k = 0; k < 2; ++k) \
;         acc[ai][bj][m][n] = __builtin_amdgcn_mfma_f32_16x16x32_bf16(Bt[n][k], At[m][k], acc[ai][bj][m][n], 0, 0, 0); __builtin_amdgcn_s_setprio(0); } while (0)
; #define GP_WAIT_V(n) asm volatile("s_waitcnt vmcnt(" #n ")" ::: "memory")
; #define GP_WAIT_L(n) asm volatile("s_waitcnt lgkmcnt(" #n ")" ::: "memory")
; #define GP_BAR __builtin_amdgcn_s_barrier()
; #define GP_SCHED __builtin_amdgcn_sched_barrier(0)
; template <class Epi, class Sched>
; __device__ __forceinline__ void gemm_phase(LAS unsigned char* lds, const int lda, const int ldb, const int K, const Sched& S, const Epi& E, const int widx) {
;     ...
;             GP_LDB(B0, 1, 0); GP_LDB(B1, 1, 1); GP_SCHED; GP_LDA(At, 1, 0); GP_STAGE(GP_SA(0, 1), a2 + hstepA, voffA);
;             GP_WAIT_V(8); GP_WAIT_L(0); GP_BAR; GP_MMA(0, 0, At, B0); GP_MMA(0, 1, At, B1); GP_BAR; GP_SCHED;
;             GP_LDA(At, 1, 1); GP_STAGE(GP_SB(1, 0), b3, voffB); GP_STAGE(GP_SB(1, 1), b3 + hstepB, voffB); GP_STAGE(GP_SA(1, 0), a3, voffA);
;             GP_WAIT_V(8); GP_WAIT_L(0); GP_BAR; GP_MMA(1, 0, At, B0); GP_MMA(1, 1, At, B1); GP_BAR; GP_SCHED;
;         }
;         if (wr == 0) GP_BAR;
	s_nop 4
	ds_read_b128 v[8:11], v157
	ds_read_b128 v[12:15], v157 offset:1024
	ds_read_b128 v[16:19], v157 offset:2048
	ds_read_b128 v[20:23], v157 offset:3072
	ds_read_b128 v[174:177], v158
	ds_read_b128 v[194:197], v158 offset:1024
	ds_read_b128 v[198:201], v158 offset:2048
	ds_read_b128 v[222:225], v158 offset:3072
	s_add_u32 s60, s54, 0x40000
	s_addc_u32 s61, s55, 0
	s_mov_b32 m0, s33
	v_lshl_add_u64 v[88:89], s[60:61], 0, v[134:135]
	ds_read_b128 v[24:27], v156 offset:32768
	ds_read_b128 v[28:31], v156 offset:33792
	ds_read_b128 v[60:63], v156 offset:34816
	ds_read_b128 v[226:229], v156 offset:35840
	ds_read_b128 v[230:233], v156 offset:36864
	ds_read_b128 v[234:237], v156 offset:37888
	ds_read_b128 v[238:241], v156 offset:38912
	ds_read_b128 v[242:245], v156 offset:39936
	global_load_lds_dwordx4 v[88:89], off
	v_lshl_add_u64 v[88:89], s[60:61], 0, v[130:131]
	s_mov_b32 m0, s34
	s_nop 0
	global_load_lds_dwordx4 v[88:89], off
	s_waitcnt vmcnt(8)
	s_waitcnt lgkmcnt(0)
	s_barrier
	s_waitcnt lgkmcnt(0)
	v_mfma_f32_16x16x32_bf16 v[64:67], v[8:11], v[24:27], v[64:67]
	v_mfma_f32_16x16x32_bf16 v[124:127], v[12:15], v[28:31], v[64:67]
	v_mfma_f32_16x16x32_bf16 v[64:67], v[16:19], v[24:27], v[68:71]
	v_mfma_f32_16x16x32_bf16 v[120:123], v[20:23], v[28:31], v[64:67]
	v_mfma_f32_16x16x32_bf16 v[64:67], v[8:11], v[60:63], v[72:75]
	v_mfma_f32_16x16x32_bf16 v[108:111], v[12:15], v[226:229], v[64:67]
	v_mfma_f32_16x16x32_bf16 v[64:67], v[16:19], v[60:63], v[76:79]
	v_mfma_f32_16x16x32_bf16 v[104:107], v[20:23], v[226:229], v[64:67]
	v_mfma_f32_16x16x32_bf16 v[64:67], v[8:11], v[230:233], v[80:83]
	v_mfma_f32_16x16x32_bf16 v[92:95], v[12:15], v[234:237], v[64:67]
	v_mfma_f32_16x16x32_bf16 v[64:67], v[16:19], v[230:233], v[84:87]
	v_mfma_f32_16x16x32_bf16 v[88:91], v[20:23], v[234:237], v[64:67]
	v_mfma_f32_16x16x32_bf16 v[64:67], v[8:11], v[238:241], v[210:213]
	v_mfma_f32_16x16x32_bf16 v[76:79], v[12:15], v[242:245], v[64:67]
	v_mfma_f32_16x16x32_bf16 v[64:67], v[16:19], v[238:241], v[214:217]
	v_mfma_f32_16x16x32_bf16 v[72:75], v[20:23], v[242:245], v[64:67]
	v_mfma_f32_16x16x32_bf16 v[64:67], v[174:177], v[24:27], v[96:99]
	v_mfma_f32_16x16x32_bf16 v[24:27], v[198:201], v[24:27], v[32:35]
	v_mfma_f32_16x16x32_bf16 v[112:115], v[222:225], v[28:31], v[24:27]
	v_mfma_f32_16x16x32_bf16 v[24:27], v[174:177], v[60:63], v[36:39]
	v_mfma_f32_16x16x32_bf16 v[100:103], v[194:197], v[226:229], v[24:27]
	v_mfma_f32_16x16x32_bf16 v[24:27], v[198:201], v[60:63], v[40:43]
	v_mfma_f32_16x16x32_bf16 v[96:99], v[222:225], v[226:229], v[24:27]
	v_mfma_f32_16x16x32_bf16 v[24:27], v[174:177], v[230:233], v[44:47]
	v_mfma_f32_16x16x32_bf16 v[84:87], v[194:197], v[234:237], v[24:27]
	v_mfma_f32_16x16x32_bf16 v[24:27], v[198:201], v[230:233], v[48:51]
	v_mfma_f32_16x16x32_bf16 v[80:83], v[222:225], v[234:237], v[24:27]
	v_mfma_f32_16x16x32_bf16 v[24:27], v[174:177], v[238:241], v[52:55]
	v_mfma_f32_16x16x32_bf16 v[68:71], v[194:197], v[242:245], v[24:27]
	v_mfma_f32_16x16x32_bf16 v[24:27], v[198:201], v[238:241], v[56:59]
	v_mfma_f32_16x16x32_bf16 v[116:119], v[194:197], v[28:31], v[64:67]
	v_mfma_f32_16x16x32_bf16 v[64:67], v[222:225], v[242:245], v[24:27]
	s_barrier
	s_mov_b32 m0, s73
	s_nop 2
	v_lshl_add_u64 v[24:25], v[164:165], 0, s[10:11]
	s_add_u32 s60, s56, 0x10080
	ds_read_b128 v[32:35], v156 offset:49152
	ds_read_b128 v[36:39], v156 offset:50176
	ds_read_b128 v[210:213], v156 offset:51200
	ds_read_b128 v[214:217], v156 offset:52224
	ds_read_b128 v[226:229], v156 offset:53248
	ds_read_b128 v[230:233], v156 offset:54272
	ds_read_b128 v[234:237], v156 offset:55296
	ds_read_b128 v[238:241], v156 offset:56320
	global_load_lds_dwordx4 v[24:25], off
	v_lshl_add_u64 v[24:25], v[246:247], 0, s[10:11]
	s_mov_b32 m0, s74
	s_addc_u32 s61, s57, 0
	global_load_lds_dwordx4 v[24:25], off
	v_lshl_add_u64 v[24:25], s[60:61], 0, v[132:133]
	s_mov_b32 m0, s75
	s_nop 0
	global_load_lds_dwordx4 v[24:25], off
	v_lshl_add_u64 v[24:25], s[60:61], 0, v[128:129]
	s_mov_b32 m0, s76
	s_nop 0
	global_load_lds_dwordx4 v[24:25], off
	v_lshl_add_u64 v[24:25], v[248:249], 0, s[10:11]
	s_mov_b32 m0, s41
	s_nop 0
	global_load_lds_dwordx4 v[24:25], off
	v_lshl_add_u64 v[24:25], v[250:251], 0, s[10:11]
	s_mov_b32 m0, s42
	s_nop 0
	global_load_lds_dwordx4 v[24:25], off
	s_waitcnt vmcnt(8)
	s_waitcnt lgkmcnt(0)
	s_barrier
	s_waitcnt lgkmcnt(0)
	v_mfma_f32_16x16x32_bf16 v[24:27], v[8:11], v[32:35], v[136:139]
	v_mfma_f32_16x16x32_bf16 v[60:63], v[12:15], v[36:39], v[24:27]
	v_mfma_f32_16x16x32_bf16 v[24:27], v[16:19], v[32:35], v[140:143]
	v_mfma_f32_16x16x32_bf16 v[56:59], v[20:23], v[36:39], v[24:27]
	v_mfma_f32_16x16x32_bf16 v[24:27], v[8:11], v[210:213], v[144:147]
	v_mfma_f32_16x16x32_bf16 v[44:47], v[12:15], v[214:217], v[24:27]
	v_mfma_f32_16x16x32_bf16 v[24:27], v[16:19], v[210:213], v[148:151]
	v_mfma_f32_16x16x32_bf16 v[40:43], v[20:23], v[214:217], v[24:27]
	v_mfma_f32_16x16x32_bf16 v[24:27], v[8:11], v[226:229], v[160:163]
	v_mfma_f32_16x16x32_bf16 v[0:3], v[8:11], v[234:237], v[0:3]
	v_mfma_f32_16x16x32_bf16 v[28:31], v[12:15], v[230:233], v[24:27]
	v_mfma_f32_16x16x32_bf16 v[24:27], v[16:19], v[226:229], v[166:169]
	v_mfma_f32_16x16x32_bf16 v[12:15], v[12:15], v[238:241], v[0:3]
	v_mfma_f32_16x16x32_bf16 v[0:3], v[16:19], v[234:237], v[4:7]
	v_mfma_f32_16x16x32_bf16 v[24:27], v[20:23], v[230:233], v[24:27]
	v_mfma_f32_16x16x32_bf16 v[8:11], v[20:23], v[238:241], v[0:3]
	v_mfma_f32_16x16x32_bf16 v[0:3], v[174:177], v[32:35], v[202:205]
	v_mfma_f32_16x16x32_bf16 v[52:55], v[194:197], v[36:39], v[0:3]
	v_mfma_f32_16x16x32_bf16 v[0:3], v[198:201], v[32:35], v[206:209]
	v_mfma_f32_16x16x32_bf16 v[48:51], v[222:225], v[36:39], v[0:3]
	v_mfma_f32_16x16x32_bf16 v[0:3], v[174:177], v[210:213], v[218:221]
	v_mfma_f32_16x16x32_bf16 v[36:39], v[194:197], v[214:217], v[0:3]
	v_mfma_f32_16x16x32_bf16 v[0:3], v[198:201], v[210:213], v[178:181]
	v_mfma_f32_16x16x32_bf16 v[32:35], v[222:225], v[214:217], v[0:3]
	v_mfma_f32_16x16x32_bf16 v[0:3], v[174:177], v[226:229], v[182:185]
	v_mfma_f32_16x16x32_bf16 v[20:23], v[194:197], v[230:233], v[0:3]
	v_mfma_f32_16x16x32_bf16 v[0:3], v[198:201], v[226:229], v[186:189]
	v_mfma_f32_16x16x32_bf16 v[16:19], v[222:225], v[230:233], v[0:3]
	v_mfma_f32_16x16x32_bf16 v[0:3], v[174:177], v[234:237], v[190:193]
	v_mfma_f32_16x16x32_bf16 v[4:7], v[194:197], v[238:241], v[0:3]
	v_mfma_f32_16x16x32_bf16 v[0:3], v[198:201], v[234:237], v[170:173]
	v_mfma_f32_16x16x32_bf16 v[0:3], v[222:225], v[238:241], v[0:3]
	s_barrier
	s_and_b64 vcc, exec, s[4:5]
	s_cbranch_vccnz .LBB0_468
	s_barrier

; #define GP_STAGE(bufoff, gbase, voff) do { _Pragma("unroll") for (int _i = 0; _i < 2; ++_i) \
;         __builtin_amdgcn_global_load_lds((const unsigned*)((const char*)(gbase) + (voff)[_i]), (LAS unsigned*)(lds + (bufoff) + ldsw + _i * 8192), 16, 0, 0); } while (0)
; #define GP_LDA(dst, b, h) do { _Pragma("unroll") for (int m = 0; m < 4; ++m) _Pragma("unroll") for (int k = 0; k < 2; ++k) dst[m][k] = *(const LAS bf16x8*)(lds + GP_SA(b, h) + aoff + m * 2048 + k * 1024); } while (0)
; #define GP_LDB(dst, b, h) do { _Pragma("unroll") for (int n = 0; n < 2; ++n) _Pragma("unroll") for (int k = 0; k < 2; ++k) dst[n][k] = *(const LAS bf16x8*)(lds + GP_SB(b, h) + boff + n * 2048 + k * 1024); } while (0)
; #define GP_MMA(ai, bj, At, Bt) do { __builtin_amdgcn_s_setprio(1); _Pragma("unroll") for (int m = 0; m < 4; ++m) _Pragma("unroll") for (int n = 0; n < 2; ++n) _Pragma("unroll") for (int k = 0; k < 2; ++k) \
;         acc[ai][bj][m][n] = __builtin_amdgcn_mfma_f32_16x16x32_bf16(Bt[n][k], At[m][k], acc[ai][bj][m][n], 0, 0, 0); __builtin_amdgcn_s_setprio(0); } while (0)
; #define GP_BAR __builtin_amdgcn_s_barrier()
; template <class Epi, class Sched>
; __device__ __forceinline__ void gemm_phase(LAS unsigned char* lds, const int lda, const int ldb, const int K, const Sched& S, const Epi& E, const int widx) {
;     ...
;         for (int t = 0; t < nt; t += 2) {
;             const bool last = (t == nt - 2);
;             const char* a1 = cA + (size_t)(t + 1) * kstep;
;             const char* a2 = last ? nA : cA + (size_t)(t + 2) * kstep; const char* b2 = last ? nB : cB + (size_t)(t + 2) * kstep;
;             const char* a3 = a2 + kstep; const char* b3 = b2 + kstep;
;             GP_LDB(B0, 0, 0); GP_LDB(B1, 0, 1); GP_SCHED; GP_LDA(At, 0, 0); GP_STAGE(GP_SA(1, 1), a1 + hstepA, voffA);
;             GP_WAIT_V(8); GP_WAIT_L(0); GP_BAR; GP_MMA(0, 0, At, B0); GP_MMA(0, 1, At, B1); GP_BAR; GP_SCHED;
;             GP_LDA(At, 0, 1); GP_STAGE(GP_SB(0, 0), b2, voffB); GP_STAGE(GP_SB(0, 1), b2 + hstepB, voffB); GP_STAGE(GP_SA(0, 0), a2, voffA);
;             GP_WAIT_V(8); GP_WAIT_L(0); GP_BAR; GP_MMA(1, 0, At, B0); GP_MMA(1, 1, At, B1); GP_BAR; GP_SCHED;
;             GP_LDB(B0, 1, 0); GP_LDB(B1, 1, 1); GP_SCHED; GP_LDA(At, 1, 0); GP_STAGE(GP_SA(0, 1), a2 + hstepA, voffA);
;             GP_WAIT_V(8); GP_WAIT_L(0); GP_BAR; GP_MMA(0, 0, At, B0); GP_MMA(0, 1, At, B1); GP_BAR; GP_SCHED;
.LBB0_545:
	v_add_u32_e32 v141, s73, v147
	ds_read_b128 v[142:145], v141
	ds_read_b128 v[152:155], v141 offset:1024
	ds_read_b128 v[156:159], v141 offset:2048
	ds_read_b128 v[160:163], v141 offset:3072
	v_add_u32_e32 v141, s74, v147
	ds_read_b128 v[166:169], v141
	ds_read_b128 v[170:173], v141 offset:1024
	ds_read_b128 v[174:177], v141 offset:2048
	ds_read_b128 v[178:181], v141 offset:3072
	s_add_u32 s34, s28, 0xfffc0080
	s_addc_u32 s35, s29, -1
	s_cmp_eq_u32 s41, 12
	s_cselect_b32 s35, s59, s35
	s_cselect_b32 s34, s58, s34
	s_cselect_b32 s67, s61, s39
	s_cselect_b32 s66, s60, s4
	s_add_i32 m0, s13, 0xc000
	ds_read_b128 v[182:185], v151
	ds_read_b128 v[186:189], v151 offset:1024
	ds_read_b128 v[190:193], v151 offset:2048
	ds_read_b128 v[194:197], v151 offset:3072
	ds_read_b128 v[198:201], v151 offset:4096
	ds_read_b128 v[202:205], v151 offset:5120
	ds_read_b128 v[206:209], v151 offset:6144
	ds_read_b128 v[210:213], v151 offset:7168
	global_load_lds_dwordx4 v136, s[28:29]
	s_add_i32 m0, s13, 0xe000
	s_nop 0
	global_load_lds_dwordx4 v138, s[28:29]
	s_waitcnt vmcnt(8)
	s_waitcnt lgkmcnt(0)
	s_barrier
	s_waitcnt lgkmcnt(0)
	v_mfma_f32_16x16x32_bf16 v[124:127], v[142:145], v[182:185], v[124:127]
	v_mfma_f32_16x16x32_bf16 v[120:123], v[156:159], v[182:185], v[120:123]
	v_mfma_f32_16x16x32_bf16 v[116:119], v[142:145], v[190:193], v[116:119]
	v_mfma_f32_16x16x32_bf16 v[112:115], v[156:159], v[190:193], v[112:115]
	v_mfma_f32_16x16x32_bf16 v[108:111], v[142:145], v[198:201], v[108:111]
	v_mfma_f32_16x16x32_bf16 v[104:107], v[156:159], v[198:201], v[104:107]
	v_mfma_f32_16x16x32_bf16 v[100:103], v[142:145], v[206:209], v[100:103]
	v_mfma_f32_16x16x32_bf16 v[96:99], v[156:159], v[206:209], v[96:99]
	v_mfma_f32_16x16x32_bf16 v[124:127], v[152:155], v[186:189], v[124:127]
	v_mfma_f32_16x16x32_bf16 v[120:123], v[160:163], v[186:189], v[120:123]
	v_mfma_f32_16x16x32_bf16 v[116:119], v[152:155], v[194:197], v[116:119]
	v_mfma_f32_16x16x32_bf16 v[112:115], v[160:163], v[194:197], v[112:115]
	v_mfma_f32_16x16x32_bf16 v[108:111], v[152:155], v[202:205], v[108:111]
	v_mfma_f32_16x16x32_bf16 v[104:107], v[160:163], v[202:205], v[104:107]
	v_mfma_f32_16x16x32_bf16 v[100:103], v[152:155], v[210:213], v[100:103]
	v_mfma_f32_16x16x32_bf16 v[96:99], v[160:163], v[210:213], v[96:99]
	v_mfma_f32_16x16x32_bf16 v[92:95], v[166:169], v[182:185], v[92:95]
	v_mfma_f32_16x16x32_bf16 v[88:91], v[174:177], v[182:185], v[88:91]
	v_mfma_f32_16x16x32_bf16 v[84:87], v[166:169], v[190:193], v[84:87]
	v_mfma_f32_16x16x32_bf16 v[80:83], v[174:177], v[190:193], v[80:83]
	v_mfma_f32_16x16x32_bf16 v[76:79], v[166:169], v[198:201], v[76:79]
	v_mfma_f32_16x16x32_bf16 v[72:75], v[174:177], v[198:201], v[72:75]
	v_mfma_f32_16x16x32_bf16 v[68:71], v[166:169], v[206:209], v[68:71]
	v_mfma_f32_16x16x32_bf16 v[64:67], v[174:177], v[206:209], v[64:67]
	v_mfma_f32_16x16x32_bf16 v[92:95], v[170:173], v[186:189], v[92:95]
	v_mfma_f32_16x16x32_bf16 v[88:91], v[178:181], v[186:189], v[88:91]
	v_mfma_f32_16x16x32_bf16 v[84:87], v[170:173], v[194:197], v[84:87]
	v_mfma_f32_16x16x32_bf16 v[80:83], v[178:181], v[194:197], v[80:83]
	v_mfma_f32_16x16x32_bf16 v[76:79], v[170:173], v[202:205], v[76:79]
	v_mfma_f32_16x16x32_bf16 v[72:75], v[178:181], v[202:205], v[72:75]
	v_mfma_f32_16x16x32_bf16 v[68:71], v[170:173], v[210:213], v[68:71]
	v_mfma_f32_16x16x32_bf16 v[64:67], v[178:181], v[210:213], v[64:67]
	s_barrier
	s_add_i32 s55, s73, s12
	s_mov_b32 m0, s55
	ds_read_b128 v[182:185], v151 offset:16384
	ds_read_b128 v[186:189], v151 offset:17408
	ds_read_b128 v[190:193], v151 offset:18432
	ds_read_b128 v[194:197], v151 offset:19456
	ds_read_b128 v[198:201], v151 offset:20480
	ds_read_b128 v[202:205], v151 offset:21504
	ds_read_b128 v[206:209], v151 offset:22528
	ds_read_b128 v[210:213], v151 offset:23552
	global_load_lds_dwordx4 v128, s[66:67]
	s_add_i32 m0, s55, 0x2000
	s_add_u32 s78, s66, 0x40000
	s_addc_u32 s79, s67, 0
	s_add_i32 s55, s74, s12
	global_load_lds_dwordx4 v130, s[66:67]
	s_mov_b32 m0, s55
	s_nop 0
	global_load_lds_dwordx4 v128, s[78:79]
	s_add_i32 m0, s55, 0x2000
	s_nop 0
	global_load_lds_dwordx4 v130, s[78:79]
	s_mov_b32 m0, s13
	s_nop 0
	global_load_lds_dwordx4 v128, s[34:35]
	s_mov_b32 m0, s33
	s_nop 0
	global_load_lds_dwordx4 v130, s[34:35]
	s_add_u32 s100, s34, 0x80
	s_addc_u32 s101, s35, 0
	s_waitcnt vmcnt(8)
	s_waitcnt lgkmcnt(0)
	s_barrier
	s_waitcnt lgkmcnt(0)
	v_mfma_f32_16x16x32_bf16 v[60:63], v[142:145], v[182:185], v[60:63]
	v_mfma_f32_16x16x32_bf16 v[56:59], v[156:159], v[182:185], v[56:59]
	v_mfma_f32_16x16x32_bf16 v[52:55], v[142:145], v[190:193], v[52:55]
	v_mfma_f32_16x16x32_bf16 v[48:51], v[156:159], v[190:193], v[48:51]
	v_mfma_f32_16x16x32_bf16 v[44:47], v[142:145], v[198:201], v[44:47]
	v_mfma_f32_16x16x32_bf16 v[40:43], v[156:159], v[198:201], v[40:43]
	v_mfma_f32_16x16x32_bf16 v[36:39], v[142:145], v[206:209], v[36:39]
	v_mfma_f32_16x16x32_bf16 v[32:35], v[156:159], v[206:209], v[32:35]
	v_mfma_f32_16x16x32_bf16 v[60:63], v[152:155], v[186:189], v[60:63]
	v_mfma_f32_16x16x32_bf16 v[56:59], v[160:163], v[186:189], v[56:59]
	v_mfma_f32_16x16x32_bf16 v[52:55], v[152:155], v[194:197], v[52:55]
	v_mfma_f32_16x16x32_bf16 v[48:51], v[160:163], v[194:197], v[48:51]
	v_mfma_f32_16x16x32_bf16 v[44:47], v[152:155], v[202:205], v[44:47]
	v_mfma_f32_16x16x32_bf16 v[40:43], v[160:163], v[202:205], v[40:43]
	v_mfma_f32_16x16x32_bf16 v[36:39], v[152:155], v[210:213], v[36:39]
	v_mfma_f32_16x16x32_bf16 v[32:35], v[160:163], v[210:213], v[32:35]
	v_mfma_f32_16x16x32_bf16 v[28:31], v[166:169], v[182:185], v[28:31]
	v_mfma_f32_16x16x32_bf16 v[24:27], v[174:177], v[182:185], v[24:27]
	v_mfma_f32_16x16x32_bf16 v[20:23], v[166:169], v[190:193], v[20:23]
	v_mfma_f32_16x16x32_bf16 v[16:19], v[174:177], v[190:193], v[16:19]
	v_mfma_f32_16x16x32_bf16 v[12:15], v[166:169], v[198:201], v[12:15]
	v_mfma_f32_16x16x32_bf16 v[8:11], v[174:177], v[198:201], v[8:11]
	v_mfma_f32_16x16x32_bf16 v[4:7], v[166:169], v[206:209], v[4:7]
	v_mfma_f32_16x16x32_bf16 v[0:3], v[174:177], v[206:209], v[0:3]
	v_mfma_f32_16x16x32_bf16 v[28:31], v[170:173], v[186:189], v[28:31]
	v_mfma_f32_16x16x32_bf16 v[24:27], v[178:181], v[186:189], v[24:27]
	v_mfma_f32_16x16x32_bf16 v[20:23], v[170:173], v[194:197], v[20:23]
	v_mfma_f32_16x16x32_bf16 v[16:19], v[178:181], v[194:197], v[16:19]
	v_mfma_f32_16x16x32_bf16 v[12:15], v[170:173], v[202:205], v[12:15]
	v_mfma_f32_16x16x32_bf16 v[8:11], v[178:181], v[202:205], v[8:11]
	v_mfma_f32_16x16x32_bf16 v[4:7], v[170:173], v[210:213], v[4:7]
	v_mfma_f32_16x16x32_bf16 v[0:3], v[178:181], v[210:213], v[0:3]
	s_barrier
; #define GP_STAGE(bufoff, gbase, voff) do { _Pragma("unroll") for (int _i = 0; _i < 2; ++_i) \
;         __builtin_amdgcn_global_load_lds((const unsigned*)((const char*)(gbase) + (voff)[_i]), (LAS unsigned*)(lds + (bufoff) + ldsw + _i * 8192), 16, 0, 0); } while (0)
; #define GP_LDA(dst, b, h) do { _Pragma("unroll") for (int m = 0; m < 4; ++m) _Pragma("unroll") for (int k = 0; k < 2; ++k) dst[m][k] = *(const LAS bf16x8*)(lds + GP_SA(b, h) + aoff + m * 2048 + k * 1024); } while (0)
; #define GP_LDB(dst, b, h) do { _Pragma("unroll") for (int n = 0; n < 2; ++n) _Pragma("unroll") for (int k = 0; k < 2; ++k) dst[n][k] = *(const LAS bf16x8*)(lds + GP_SB(b, h) + boff + n * 2048 + k * 1024); } while (0)
; #define GP_MMA(ai, bj, At, Bt) do { __builtin_amdgcn_s_setprio(1); _Pragma("unroll") for (int m = 0; m < 4; ++m) _Pragma("unroll") for (int n = 0; n < 2; ++n) _Pragma("unroll") for (int k = 0; k < 2; ++k) \
;         acc[ai][bj][m][n] = __builtin_amdgcn_mfma_f32_16x16x32_bf16(Bt[n][k], At[m][k], acc[ai][bj][m][n], 0, 0, 0); __builtin_amdgcn_s_setprio(0); } while (0)
; #define GP_WAIT_V(n) asm volatile("s_waitcnt vmcnt(" #n ")" ::: "memory")
; #define GP_WAIT_L(n) asm volatile("s_waitcnt lgkmcnt(" #n ")" ::: "memory")
; #define GP_BAR __builtin_amdgcn_s_barrier()
; #define GP_SCHED __builtin_amdgcn_sched_barrier(0)
; template <class Epi, class Sched>
; __device__ __forceinline__ void gemm_phase(LAS unsigned char* lds, const int lda, const int ldb, const int K, const Sched& S, const Epi& E, const int widx) {
;     ...
;             GP_LDB(B0, 1, 0); GP_LDB(B1, 1, 1); GP_SCHED; GP_LDA(At, 1, 0); GP_STAGE(GP_SA(0, 1), a2 + hstepA, voffA);
;             GP_WAIT_V(8); GP_WAIT_L(0); GP_BAR; GP_MMA(0, 0, At, B0); GP_MMA(0, 1, At, B1); GP_BAR; GP_SCHED;
;             GP_LDA(At, 1, 1); GP_STAGE(GP_SB(1, 0), b3, voffB); GP_STAGE(GP_SB(1, 1), b3 + hstepB, voffB); GP_STAGE(GP_SA(1, 0), a3, voffA);
;             GP_WAIT_V(8); GP_WAIT_L(0); GP_BAR; GP_MMA(1, 0, At, B0); GP_MMA(1, 1, At, B1); GP_BAR; GP_SCHED;
;         }
;         if (wr == 0) GP_BAR;
	s_add_i32 s55, 0, 0x18000
	v_add_u32_e32 v141, s55, v147
	s_add_i32 s57, 0, 0x1c000
	ds_read_b128 v[142:145], v141
	ds_read_b128 v[152:155], v141 offset:1024
	ds_read_b128 v[156:159], v141 offset:2048
	ds_read_b128 v[160:163], v141 offset:3072
	v_add_u32_e32 v141, s57, v147
	ds_read_b128 v[166:169], v141
	ds_read_b128 v[170:173], v141 offset:1024
	ds_read_b128 v[174:177], v141 offset:2048
	ds_read_b128 v[178:181], v141 offset:3072
	s_add_u32 s34, s34, 0x40000
	s_addc_u32 s35, s35, 0
	s_mov_b32 m0, s65
	ds_read_b128 v[182:185], v151 offset:32768
	ds_read_b128 v[186:189], v151 offset:33792
	ds_read_b128 v[190:193], v151 offset:34816
	ds_read_b128 v[194:197], v151 offset:35840
	ds_read_b128 v[198:201], v151 offset:36864
	ds_read_b128 v[202:205], v151 offset:37888
	ds_read_b128 v[206:209], v151 offset:38912
	ds_read_b128 v[210:213], v151 offset:39936
	global_load_lds_dwordx4 v128, s[34:35]
	s_mov_b32 m0, s70
	s_nop 0
	global_load_lds_dwordx4 v130, s[34:35]
	s_waitcnt vmcnt(8)
	s_waitcnt lgkmcnt(0)
	s_barrier
	s_waitcnt lgkmcnt(0)
	v_mfma_f32_16x16x32_bf16 v[124:127], v[142:145], v[182:185], v[124:127]
	v_mfma_f32_16x16x32_bf16 v[120:123], v[156:159], v[182:185], v[120:123]
	v_mfma_f32_16x16x32_bf16 v[116:119], v[142:145], v[190:193], v[116:119]
	v_mfma_f32_16x16x32_bf16 v[112:115], v[156:159], v[190:193], v[112:115]
	v_mfma_f32_16x16x32_bf16 v[108:111], v[142:145], v[198:201], v[108:111]
	v_mfma_f32_16x16x32_bf16 v[104:107], v[156:159], v[198:201], v[104:107]
	v_mfma_f32_16x16x32_bf16 v[100:103], v[142:145], v[206:209], v[100:103]
	v_mfma_f32_16x16x32_bf16 v[96:99], v[156:159], v[206:209], v[96:99]
	v_mfma_f32_16x16x32_bf16 v[124:127], v[152:155], v[186:189], v[124:127]
	v_mfma_f32_16x16x32_bf16 v[120:123], v[160:163], v[186:189], v[120:123]
	v_mfma_f32_16x16x32_bf16 v[116:119], v[152:155], v[194:197], v[116:119]
	v_mfma_f32_16x16x32_bf16 v[112:115], v[160:163], v[194:197], v[112:115]
	v_mfma_f32_16x16x32_bf16 v[108:111], v[152:155], v[202:205], v[108:111]
	v_mfma_f32_16x16x32_bf16 v[104:107], v[160:163], v[202:205], v[104:107]
	v_mfma_f32_16x16x32_bf16 v[100:103], v[152:155], v[210:213], v[100:103]
	v_mfma_f32_16x16x32_bf16 v[96:99], v[160:163], v[210:213], v[96:99]
	v_mfma_f32_16x16x32_bf16 v[92:95], v[166:169], v[182:185], v[92:95]
	v_mfma_f32_16x16x32_bf16 v[88:91], v[174:177], v[182:185], v[88:91]
	v_mfma_f32_16x16x32_bf16 v[84:87], v[166:169], v[190:193], v[84:87]
	v_mfma_f32_16x16x32_bf16 v[80:83], v[174:177], v[190:193], v[80:83]
	v_mfma_f32_16x16x32_bf16 v[76:79], v[166:169], v[198:201], v[76:79]
	v_mfma_f32_16x16x32_bf16 v[72:75], v[174:177], v[198:201], v[72:75]
	v_mfma_f32_16x16x32_bf16 v[68:71], v[166:169], v[206:209], v[68:71]
	v_mfma_f32_16x16x32_bf16 v[64:67], v[174:177], v[206:209], v[64:67]
	v_mfma_f32_16x16x32_bf16 v[92:95], v[170:173], v[186:189], v[92:95]
	v_mfma_f32_16x16x32_bf16 v[88:91], v[178:181], v[186:189], v[88:91]
	v_mfma_f32_16x16x32_bf16 v[84:87], v[170:173], v[194:197], v[84:87]
	v_mfma_f32_16x16x32_bf16 v[80:83], v[178:181], v[194:197], v[80:83]
	v_mfma_f32_16x16x32_bf16 v[76:79], v[170:173], v[202:205], v[76:79]
	v_mfma_f32_16x16x32_bf16 v[72:75], v[178:181], v[202:205], v[72:75]
	v_mfma_f32_16x16x32_bf16 v[68:71], v[170:173], v[210:213], v[68:71]
	v_mfma_f32_16x16x32_bf16 v[64:67], v[178:181], v[210:213], v[64:67]
	s_barrier
	s_add_i32 s34, s55, s12
	s_add_u32 s98, s66, 0x80
	s_addc_u32 s99, s67, 0
	s_mov_b32 m0, s34
	ds_read_b128 v[182:185], v151 offset:49152
	ds_read_b128 v[186:189], v151 offset:50176
	ds_read_b128 v[190:193], v151 offset:51200
	ds_read_b128 v[194:197], v151 offset:52224
	ds_read_b128 v[198:201], v151 offset:53248
	ds_read_b128 v[202:205], v151 offset:54272
	ds_read_b128 v[206:209], v151 offset:55296
	ds_read_b128 v[210:213], v151 offset:56320
	global_load_lds_dwordx4 v128, s[98:99]
	s_add_i32 m0, s34, 0x2000
	s_add_u32 s34, s66, 0x40080
	s_addc_u32 s35, s67, 0
	s_add_i32 s55, s57, s12
	global_load_lds_dwordx4 v130, s[98:99]
	s_mov_b32 m0, s55
	s_nop 0
	global_load_lds_dwordx4 v128, s[34:35]
	s_add_i32 m0, s55, 0x2000
	s_nop 0
	global_load_lds_dwordx4 v130, s[34:35]
	s_mov_b32 m0, s71
	s_nop 0
	global_load_lds_dwordx4 v128, s[100:101]
	s_mov_b32 m0, s72
	s_nop 0
	global_load_lds_dwordx4 v130, s[100:101]
	s_waitcnt vmcnt(8)
	s_waitcnt lgkmcnt(0)
	s_barrier
	s_waitcnt lgkmcnt(0)
	v_mfma_f32_16x16x32_bf16 v[60:63], v[142:145], v[182:185], v[60:63]
	v_mfma_f32_16x16x32_bf16 v[56:59], v[156:159], v[182:185], v[56:59]
	v_mfma_f32_16x16x32_bf16 v[52:55], v[142:145], v[190:193], v[52:55]
	v_mfma_f32_16x16x32_bf16 v[48:51], v[156:159], v[190:193], v[48:51]
	v_mfma_f32_16x16x32_bf16 v[44:47], v[142:145], v[198:201], v[44:47]
	v_mfma_f32_16x16x32_bf16 v[40:43], v[156:159], v[198:201], v[40:43]
	v_mfma_f32_16x16x32_bf16 v[36:39], v[142:145], v[206:209], v[36:39]
	v_mfma_f32_16x16x32_bf16 v[32:35], v[156:159], v[206:209], v[32:35]
	v_mfma_f32_16x16x32_bf16 v[60:63], v[152:155], v[186:189], v[60:63]
	v_mfma_f32_16x16x32_bf16 v[56:59], v[160:163], v[186:189], v[56:59]
	v_mfma_f32_16x16x32_bf16 v[52:55], v[152:155], v[194:197], v[52:55]
	v_mfma_f32_16x16x32_bf16 v[48:51], v[160:163], v[194:197], v[48:51]
	v_mfma_f32_16x16x32_bf16 v[44:47], v[152:155], v[202:205], v[44:47]
	v_mfma_f32_16x16x32_bf16 v[40:43], v[160:163], v[202:205], v[40:43]
	v_mfma_f32_16x16x32_bf16 v[36:39], v[152:155], v[210:213], v[36:39]
	v_mfma_f32_16x16x32_bf16 v[32:35], v[160:163], v[210:213], v[32:35]
	v_mfma_f32_16x16x32_bf16 v[28:31], v[166:169], v[182:185], v[28:31]
	v_mfma_f32_16x16x32_bf16 v[24:27], v[174:177], v[182:185], v[24:27]
	v_mfma_f32_16x16x32_bf16 v[20:23], v[166:169], v[190:193], v[20:23]
	v_mfma_f32_16x16x32_bf16 v[16:19], v[174:177], v[190:193], v[16:19]
	v_mfma_f32_16x16x32_bf16 v[12:15], v[166:169], v[198:201], v[12:15]
	v_mfma_f32_16x16x32_bf16 v[8:11], v[174:177], v[198:201], v[8:11]
	v_mfma_f32_16x16x32_bf16 v[4:7], v[166:169], v[206:209], v[4:7]
	v_mfma_f32_16x16x32_bf16 v[0:3], v[174:177], v[206:209], v[0:3]
	v_mfma_f32_16x16x32_bf16 v[28:31], v[170:173], v[186:189], v[28:31]
	v_mfma_f32_16x16x32_bf16 v[24:27], v[178:181], v[186:189], v[24:27]
	v_mfma_f32_16x16x32_bf16 v[20:23], v[170:173], v[194:197], v[20:23]
	v_mfma_f32_16x16x32_bf16 v[16:19], v[178:181], v[194:197], v[16:19]
	v_mfma_f32_16x16x32_bf16 v[12:15], v[170:173], v[202:205], v[12:15]
	v_mfma_f32_16x16x32_bf16 v[8:11], v[178:181], v[202:205], v[8:11]
	v_mfma_f32_16x16x32_bf16 v[4:7], v[170:173], v[210:213], v[4:7]
	v_mfma_f32_16x16x32_bf16 v[0:3], v[178:181], v[210:213], v[0:3]
	s_barrier
	s_add_i32 s41, s41, 2
	s_add_u32 s28, s28, 0x100
	s_addc_u32 s29, s29, 0
	s_add_u32 s4, s4, 0x100
	s_addc_u32 s39, s39, 0
	s_cmp_gt_u32 s41, 13
	s_cbranch_scc0 .LBB0_545
	s_and_b64 vcc, exec, s[10:11]
	s_cbranch_vccz .LBB0_548
	s_barrier

; #define GP_STAGE(bufoff, gbase, voff) do { _Pragma("unroll") for (int _i = 0; _i < 2; ++_i) \
;         __builtin_amdgcn_global_load_lds((const unsigned*)((const char*)(gbase) + (voff)[_i]), (LAS unsigned*)(lds + (bufoff) + ldsw + _i * 8192), 16, 0, 0); } while (0)
; #define GP_LDA(dst, b, h) do { _Pragma("unroll") for (int m = 0; m < 4; ++m) _Pragma("unroll") for (int k = 0; k < 2; ++k) dst[m][k] = *(const LAS bf16x8*)(lds + GP_SA(b, h) + aoff + m * 2048 + k * 1024); } while (0)
; #define GP_LDB(dst, b, h) do { _Pragma("unroll") for (int n = 0; n < 2; ++n) _Pragma("unroll") for (int k = 0; k < 2; ++k) dst[n][k] = *(const LAS bf16x8*)(lds + GP_SB(b, h) + boff + n * 2048 + k * 1024); } while (0)
; #define GP_MMA(ai, bj, At, Bt) do { __builtin_amdgcn_s_setprio(1); _Pragma("unroll") for (int m = 0; m < 4; ++m) _Pragma("unroll") for (int n = 0; n < 2; ++n) _Pragma("unroll") for (int k = 0; k < 2; ++k) \
;         acc[ai][bj][m][n] = __builtin_amdgcn_mfma_f32_16x16x32_bf16(Bt[n][k], At[m][k], acc[ai][bj][m][n], 0, 0, 0); __builtin_amdgcn_s_setprio(0); } while (0)
; #define GP_WAIT_V(n) asm volatile("s_waitcnt vmcnt(" #n ")" ::: "memory")
; #define GP_WAIT_L(n) asm volatile("s_waitcnt lgkmcnt(" #n ")" ::: "memory")
; #define GP_BAR __builtin_amdgcn_s_barrier()
; #define GP_SCHED __builtin_amdgcn_sched_barrier(0)
; template <class Epi, class Sched>
; __device__ __forceinline__ void gemm_phase(LAS unsigned char* lds, const int lda, const int ldb, const int K, const Sched& S, const Epi& E, const int widx) {
;     ...
;             GP_LDB(B0, 0, 0); GP_LDB(B1, 0, 1); GP_SCHED; GP_LDA(At, 0, 0); GP_STAGE(GP_SA(1, 1), a1 + hstepA, voffA);
;             GP_WAIT_V(8); GP_WAIT_L(0); GP_BAR; GP_MMA(0, 0, At, B0); GP_MMA(0, 1, At, B1); GP_BAR; GP_SCHED;
;             GP_LDA(At, 0, 1); GP_STAGE(GP_SB(0, 0), b2, voffB); GP_STAGE(GP_SB(0, 1), b2 + hstepB, voffB); GP_STAGE(GP_SA(0, 0), a2, voffA);
;             GP_WAIT_V(8); GP_WAIT_L(0); GP_BAR; GP_MMA(1, 0, At, B0); GP_MMA(1, 1, At, B1); GP_BAR; GP_SCHED;
.LBB0_629:
	ds_read_b128 v[128:131], v198
	ds_read_b128 v[132:135], v198 offset:1024
	ds_read_b128 v[136:139], v198 offset:2048
	ds_read_b128 v[140:143], v198 offset:3072
	ds_read_b128 v[144:147], v199
	ds_read_b128 v[148:151], v199 offset:1024
	ds_read_b128 v[152:155], v199 offset:2048
	ds_read_b128 v[156:159], v199 offset:3072
	s_add_u32 s28, s40, 0xfffc0080
	s_addc_u32 s29, s41, -1
	s_cmp_eq_u32 s43, 12
	s_cselect_b32 s35, s31, s29
	s_cselect_b32 s34, s30, s28
	s_cselect_b32 s29, s37, s42
	s_cselect_b32 s28, s36, s21
	v_lshl_add_u64 v[214:215], s[40:41], 0, v[186:187]
	s_add_i32 m0, s13, 0xc000
	ds_read_b128 v[160:163], v200
	ds_read_b128 v[164:167], v200 offset:1024
	ds_read_b128 v[168:171], v200 offset:2048
	ds_read_b128 v[172:175], v200 offset:3072
	ds_read_b128 v[190:193], v200 offset:4096
	ds_read_b128 v[202:205], v200 offset:5120
	ds_read_b128 v[206:209], v200 offset:6144
	ds_read_b128 v[210:213], v200 offset:7168
	global_load_lds_dwordx4 v[214:215], off
	v_lshl_add_u64 v[214:215], s[40:41], 0, v[188:189]
	s_add_i32 m0, s13, 0xe000
	s_nop 0
	global_load_lds_dwordx4 v[214:215], off
	s_waitcnt vmcnt(8)
	s_waitcnt lgkmcnt(0)
	s_barrier
	s_waitcnt lgkmcnt(0)
	v_mfma_f32_16x16x32_bf16 v[124:127], v[128:131], v[160:163], v[124:127]
	v_mfma_f32_16x16x32_bf16 v[120:123], v[136:139], v[160:163], v[120:123]
	v_mfma_f32_16x16x32_bf16 v[108:111], v[128:131], v[168:171], v[108:111]
	v_mfma_f32_16x16x32_bf16 v[104:107], v[136:139], v[168:171], v[104:107]
	v_mfma_f32_16x16x32_bf16 v[92:95], v[128:131], v[190:193], v[92:95]
	v_mfma_f32_16x16x32_bf16 v[88:91], v[136:139], v[190:193], v[88:91]
	v_mfma_f32_16x16x32_bf16 v[76:79], v[128:131], v[206:209], v[76:79]
	v_mfma_f32_16x16x32_bf16 v[72:75], v[136:139], v[206:209], v[72:75]
	v_mfma_f32_16x16x32_bf16 v[124:127], v[132:135], v[164:167], v[124:127]
	v_mfma_f32_16x16x32_bf16 v[120:123], v[140:143], v[164:167], v[120:123]
	v_mfma_f32_16x16x32_bf16 v[108:111], v[132:135], v[172:175], v[108:111]
	v_mfma_f32_16x16x32_bf16 v[104:107], v[140:143], v[172:175], v[104:107]
	v_mfma_f32_16x16x32_bf16 v[92:95], v[132:135], v[202:205], v[92:95]
	v_mfma_f32_16x16x32_bf16 v[88:91], v[140:143], v[202:205], v[88:91]
	v_mfma_f32_16x16x32_bf16 v[76:79], v[132:135], v[210:213], v[76:79]
	v_mfma_f32_16x16x32_bf16 v[72:75], v[140:143], v[210:213], v[72:75]
	v_mfma_f32_16x16x32_bf16 v[116:119], v[144:147], v[160:163], v[116:119]
	v_mfma_f32_16x16x32_bf16 v[112:115], v[152:155], v[160:163], v[112:115]
	v_mfma_f32_16x16x32_bf16 v[100:103], v[144:147], v[168:171], v[100:103]
	v_mfma_f32_16x16x32_bf16 v[96:99], v[152:155], v[168:171], v[96:99]
	v_mfma_f32_16x16x32_bf16 v[84:87], v[144:147], v[190:193], v[84:87]
	v_mfma_f32_16x16x32_bf16 v[80:83], v[152:155], v[190:193], v[80:83]
	v_mfma_f32_16x16x32_bf16 v[68:71], v[144:147], v[206:209], v[68:71]
	v_mfma_f32_16x16x32_bf16 v[64:67], v[152:155], v[206:209], v[64:67]
	v_mfma_f32_16x16x32_bf16 v[116:119], v[148:151], v[164:167], v[116:119]
	v_mfma_f32_16x16x32_bf16 v[112:115], v[156:159], v[164:167], v[112:115]
	v_mfma_f32_16x16x32_bf16 v[100:103], v[148:151], v[172:175], v[100:103]
	v_mfma_f32_16x16x32_bf16 v[96:99], v[156:159], v[172:175], v[96:99]
	v_mfma_f32_16x16x32_bf16 v[84:87], v[148:151], v[202:205], v[84:87]
	v_mfma_f32_16x16x32_bf16 v[80:83], v[156:159], v[202:205], v[80:83]
	v_mfma_f32_16x16x32_bf16 v[68:71], v[148:151], v[210:213], v[68:71]
	v_mfma_f32_16x16x32_bf16 v[64:67], v[156:159], v[210:213], v[64:67]
	s_barrier
	s_add_i32 s57, s51, s12
	v_lshl_add_u64 v[214:215], s[28:29], 0, v[176:177]
	s_mov_b32 m0, s57
	ds_read_b128 v[160:163], v200 offset:16384
	ds_read_b128 v[164:167], v200 offset:17408
	ds_read_b128 v[168:171], v200 offset:18432
	ds_read_b128 v[172:175], v200 offset:19456
	ds_read_b128 v[190:193], v200 offset:20480
	ds_read_b128 v[202:205], v200 offset:21504
	ds_read_b128 v[206:209], v200 offset:22528
	ds_read_b128 v[210:213], v200 offset:23552
	global_load_lds_dwordx4 v[214:215], off
	s_add_i32 m0, s57, 0x2000
	s_add_u32 s58, s28, 0x40000
	v_lshl_add_u64 v[216:217], s[28:29], 0, v[178:179]
	s_addc_u32 s59, s29, 0
	s_add_i32 s57, s52, s12
	global_load_lds_dwordx4 v[216:217], off
	v_lshl_add_u64 v[218:219], s[58:59], 0, v[176:177]
	s_mov_b32 m0, s57
	v_lshl_add_u64 v[220:221], s[34:35], 0, v[178:179]
	global_load_lds_dwordx4 v[218:219], off
	v_lshl_add_u64 v[218:219], s[58:59], 0, v[178:179]
	s_add_i32 m0, s57, 0x2000
	s_nop 0
	global_load_lds_dwordx4 v[218:219], off
	v_lshl_add_u64 v[218:219], s[34:35], 0, v[176:177]
	s_mov_b32 m0, s13
	s_nop 0
	global_load_lds_dwordx4 v[218:219], off
	s_mov_b32 m0, s33
	s_nop 0
	global_load_lds_dwordx4 v[220:221], off
	s_waitcnt vmcnt(8)
	s_waitcnt lgkmcnt(0)
	s_barrier
; #define GP_STAGE(bufoff, gbase, voff) do { _Pragma("unroll") for (int _i = 0; _i < 2; ++_i) \
;         __builtin_amdgcn_global_load_lds((const unsigned*)((const char*)(gbase) + (voff)[_i]), (LAS unsigned*)(lds + (bufoff) + ldsw + _i * 8192), 16, 0, 0); } while (0)
; #define GP_LDA(dst, b, h) do { _Pragma("unroll") for (int m = 0; m < 4; ++m) _Pragma("unroll") for (int k = 0; k < 2; ++k) dst[m][k] = *(const LAS bf16x8*)(lds + GP_SA(b, h) + aoff + m * 2048 + k * 1024); } while (0)
; #define GP_LDB(dst, b, h) do { _Pragma("unroll") for (int n = 0; n < 2; ++n) _Pragma("unroll") for (int k = 0; k < 2; ++k) dst[n][k] = *(const LAS bf16x8*)(lds + GP_SB(b, h) + boff + n * 2048 + k * 1024); } while (0)
; #define GP_MMA(ai, bj, At, Bt) do { __builtin_amdgcn_s_setprio(1); _Pragma("unroll") for (int m = 0; m < 4; ++m) _Pragma("unroll") for (int n = 0; n < 2; ++n) _Pragma("unroll") for (int k = 0; k < 2; ++k) \
;         acc[ai][bj][m][n] = __builtin_amdgcn_mfma_f32_16x16x32_bf16(Bt[n][k], At[m][k], acc[ai][bj][m][n], 0, 0, 0); __builtin_amdgcn_s_setprio(0); } while (0)
; #define GP_WAIT_V(n) asm volatile("s_waitcnt vmcnt(" #n ")" ::: "memory")
; #define GP_WAIT_L(n) asm volatile("s_waitcnt lgkmcnt(" #n ")" ::: "memory")
; #define GP_BAR __builtin_amdgcn_s_barrier()
; #define GP_SCHED __builtin_amdgcn_sched_barrier(0)
; template <class Epi, class Sched>
; __device__ __forceinline__ void gemm_phase(LAS unsigned char* lds, const int lda, const int ldb, const int K, const Sched& S, const Epi& E, const int widx) {
;     ...
;             GP_WAIT_V(8); GP_WAIT_L(0); GP_BAR; GP_MMA(1, 0, At, B0); GP_MMA(1, 1, At, B1); GP_BAR; GP_SCHED;
;             GP_LDB(B0, 1, 0); GP_LDB(B1, 1, 1); GP_SCHED; GP_LDA(At, 1, 0); GP_STAGE(GP_SA(0, 1), a2 + hstepA, voffA);
;             GP_WAIT_V(8); GP_WAIT_L(0); GP_BAR; GP_MMA(0, 0, At, B0); GP_MMA(0, 1, At, B1); GP_BAR; GP_SCHED;
	s_waitcnt lgkmcnt(0)
	v_mfma_f32_16x16x32_bf16 v[60:63], v[128:131], v[160:163], v[60:63]
	v_mfma_f32_16x16x32_bf16 v[56:59], v[136:139], v[160:163], v[56:59]
	v_mfma_f32_16x16x32_bf16 v[44:47], v[128:131], v[168:171], v[44:47]
	v_mfma_f32_16x16x32_bf16 v[40:43], v[136:139], v[168:171], v[40:43]
	v_mfma_f32_16x16x32_bf16 v[28:31], v[128:131], v[190:193], v[28:31]
	v_mfma_f32_16x16x32_bf16 v[24:27], v[136:139], v[190:193], v[24:27]
	v_mfma_f32_16x16x32_bf16 v[12:15], v[128:131], v[206:209], v[12:15]
	v_mfma_f32_16x16x32_bf16 v[8:11], v[136:139], v[206:209], v[8:11]
	v_mfma_f32_16x16x32_bf16 v[60:63], v[132:135], v[164:167], v[60:63]
	v_mfma_f32_16x16x32_bf16 v[56:59], v[140:143], v[164:167], v[56:59]
	v_mfma_f32_16x16x32_bf16 v[44:47], v[132:135], v[172:175], v[44:47]
	v_mfma_f32_16x16x32_bf16 v[40:43], v[140:143], v[172:175], v[40:43]
	v_mfma_f32_16x16x32_bf16 v[28:31], v[132:135], v[202:205], v[28:31]
	v_mfma_f32_16x16x32_bf16 v[24:27], v[140:143], v[202:205], v[24:27]
	v_mfma_f32_16x16x32_bf16 v[12:15], v[132:135], v[210:213], v[12:15]
	v_mfma_f32_16x16x32_bf16 v[8:11], v[140:143], v[210:213], v[8:11]
	v_mfma_f32_16x16x32_bf16 v[52:55], v[144:147], v[160:163], v[52:55]
	v_mfma_f32_16x16x32_bf16 v[48:51], v[152:155], v[160:163], v[48:51]
	v_mfma_f32_16x16x32_bf16 v[36:39], v[144:147], v[168:171], v[36:39]
	v_mfma_f32_16x16x32_bf16 v[32:35], v[152:155], v[168:171], v[32:35]
	v_mfma_f32_16x16x32_bf16 v[20:23], v[144:147], v[190:193], v[20:23]
	v_mfma_f32_16x16x32_bf16 v[16:19], v[152:155], v[190:193], v[16:19]
	v_mfma_f32_16x16x32_bf16 v[4:7], v[144:147], v[206:209], v[4:7]
	v_mfma_f32_16x16x32_bf16 v[0:3], v[152:155], v[206:209], v[0:3]
	v_mfma_f32_16x16x32_bf16 v[52:55], v[148:151], v[164:167], v[52:55]
	v_mfma_f32_16x16x32_bf16 v[48:51], v[156:159], v[164:167], v[48:51]
	v_mfma_f32_16x16x32_bf16 v[36:39], v[148:151], v[172:175], v[36:39]
	v_mfma_f32_16x16x32_bf16 v[32:35], v[156:159], v[172:175], v[32:35]
	v_mfma_f32_16x16x32_bf16 v[20:23], v[148:151], v[202:205], v[20:23]
	v_mfma_f32_16x16x32_bf16 v[16:19], v[156:159], v[202:205], v[16:19]
	v_mfma_f32_16x16x32_bf16 v[4:7], v[148:151], v[210:213], v[4:7]
	v_mfma_f32_16x16x32_bf16 v[0:3], v[156:159], v[210:213], v[0:3]
	s_barrier
	s_add_i32 s57, 0, 0x18000
	s_add_i32 s58, 0, 0x1c000
	v_add_u32_e32 v140, s57, v194
	v_add_u32_e32 v156, s58, v194
	ds_read_b128 v[128:131], v140
	ds_read_b128 v[132:135], v140 offset:1024
	ds_read_b128 v[136:139], v140 offset:2048
	ds_read_b128 v[140:143], v140 offset:3072
	ds_read_b128 v[144:147], v156
	ds_read_b128 v[148:151], v156 offset:1024
	ds_read_b128 v[152:155], v156 offset:2048
	ds_read_b128 v[156:159], v156 offset:3072
	s_add_u32 s34, s34, 0x40000
	s_addc_u32 s35, s35, 0
	s_mov_b32 m0, s39
	v_lshl_add_u64 v[222:223], s[34:35], 0, v[176:177]
	ds_read_b128 v[160:163], v200 offset:32768
	ds_read_b128 v[164:167], v200 offset:33792
	ds_read_b128 v[168:171], v200 offset:34816
	ds_read_b128 v[172:175], v200 offset:35840
	ds_read_b128 v[190:193], v200 offset:36864
	ds_read_b128 v[202:205], v200 offset:37888
	ds_read_b128 v[206:209], v200 offset:38912
	ds_read_b128 v[210:213], v200 offset:39936
	global_load_lds_dwordx4 v[222:223], off
	v_lshl_add_u64 v[222:223], s[34:35], 0, v[178:179]
	s_mov_b32 m0, s44
	s_nop 0
	global_load_lds_dwordx4 v[222:223], off
	s_waitcnt vmcnt(8)
	s_waitcnt lgkmcnt(0)
	s_barrier
	s_waitcnt lgkmcnt(0)
	v_mfma_f32_16x16x32_bf16 v[124:127], v[128:131], v[160:163], v[124:127]
	v_mfma_f32_16x16x32_bf16 v[120:123], v[136:139], v[160:163], v[120:123]
	v_mfma_f32_16x16x32_bf16 v[108:111], v[128:131], v[168:171], v[108:111]
	v_mfma_f32_16x16x32_bf16 v[104:107], v[136:139], v[168:171], v[104:107]
	v_mfma_f32_16x16x32_bf16 v[92:95], v[128:131], v[190:193], v[92:95]
	v_mfma_f32_16x16x32_bf16 v[88:91], v[136:139], v[190:193], v[88:91]
	v_mfma_f32_16x16x32_bf16 v[76:79], v[128:131], v[206:209], v[76:79]
	v_mfma_f32_16x16x32_bf16 v[72:75], v[136:139], v[206:209], v[72:75]
	v_mfma_f32_16x16x32_bf16 v[124:127], v[132:135], v[164:167], v[124:127]
	v_mfma_f32_16x16x32_bf16 v[120:123], v[140:143], v[164:167], v[120:123]
	v_mfma_f32_16x16x32_bf16 v[108:111], v[132:135], v[172:175], v[108:111]
	v_mfma_f32_16x16x32_bf16 v[104:107], v[140:143], v[172:175], v[104:107]
	v_mfma_f32_16x16x32_bf16 v[92:95], v[132:135], v[202:205], v[92:95]
	v_mfma_f32_16x16x32_bf16 v[88:91], v[140:143], v[202:205], v[88:91]
	v_mfma_f32_16x16x32_bf16 v[76:79], v[132:135], v[210:213], v[76:79]
	v_mfma_f32_16x16x32_bf16 v[72:75], v[140:143], v[210:213], v[72:75]
	v_mfma_f32_16x16x32_bf16 v[116:119], v[144:147], v[160:163], v[116:119]
	v_mfma_f32_16x16x32_bf16 v[112:115], v[152:155], v[160:163], v[112:115]
	v_mfma_f32_16x16x32_bf16 v[100:103], v[144:147], v[168:171], v[100:103]
	v_mfma_f32_16x16x32_bf16 v[96:99], v[152:155], v[168:171], v[96:99]
	v_mfma_f32_16x16x32_bf16 v[84:87], v[144:147], v[190:193], v[84:87]
	v_mfma_f32_16x16x32_bf16 v[80:83], v[152:155], v[190:193], v[80:83]
	v_mfma_f32_16x16x32_bf16 v[68:71], v[144:147], v[206:209], v[68:71]
	v_mfma_f32_16x16x32_bf16 v[64:67], v[152:155], v[206:209], v[64:67]
	v_mfma_f32_16x16x32_bf16 v[116:119], v[148:151], v[164:167], v[116:119]
	v_mfma_f32_16x16x32_bf16 v[112:115], v[156:159], v[164:167], v[112:115]
	v_mfma_f32_16x16x32_bf16 v[100:103], v[148:151], v[172:175], v[100:103]
	v_mfma_f32_16x16x32_bf16 v[96:99], v[156:159], v[172:175], v[96:99]
	v_mfma_f32_16x16x32_bf16 v[84:87], v[148:151], v[202:205], v[84:87]
	v_mfma_f32_16x16x32_bf16 v[80:83], v[156:159], v[202:205], v[80:83]
	v_mfma_f32_16x16x32_bf16 v[68:71], v[148:151], v[210:213], v[68:71]
	v_mfma_f32_16x16x32_bf16 v[64:67], v[156:159], v[210:213], v[64:67]
	s_barrier
; #define GP_STAGE(bufoff, gbase, voff) do { _Pragma("unroll") for (int _i = 0; _i < 2; ++_i) \
;         __builtin_amdgcn_global_load_lds((const unsigned*)((const char*)(gbase) + (voff)[_i]), (LAS unsigned*)(lds + (bufoff) + ldsw + _i * 8192), 16, 0, 0); } while (0)
; #define GP_LDA(dst, b, h) do { _Pragma("unroll") for (int m = 0; m < 4; ++m) _Pragma("unroll") for (int k = 0; k < 2; ++k) dst[m][k] = *(const LAS bf16x8*)(lds + GP_SA(b, h) + aoff + m * 2048 + k * 1024); } while (0)
; #define GP_MMA(ai, bj, At, Bt) do { __builtin_amdgcn_s_setprio(1); _Pragma("unroll") for (int m = 0; m < 4; ++m) _Pragma("unroll") for (int n = 0; n < 2; ++n) _Pragma("unroll") for (int k = 0; k < 2; ++k) \
;         acc[ai][bj][m][n] = __builtin_amdgcn_mfma_f32_16x16x32_bf16(Bt[n][k], At[m][k], acc[ai][bj][m][n], 0, 0, 0); __builtin_amdgcn_s_setprio(0); } while (0)
; #define GP_WAIT_V(n) asm volatile("s_waitcnt vmcnt(" #n ")" ::: "memory")
; #define GP_WAIT_L(n) asm volatile("s_waitcnt lgkmcnt(" #n ")" ::: "memory")
; #define GP_BAR __builtin_amdgcn_s_barrier()
; #define GP_SCHED __builtin_amdgcn_sched_barrier(0)
; template <class Epi, class Sched>
; __device__ __forceinline__ void gemm_phase(LAS unsigned char* lds, const int lda, const int ldb, const int K, const Sched& S, const Epi& E, const int widx) {
;     ...
;             GP_LDA(At, 1, 1); GP_STAGE(GP_SB(1, 0), b3, voffB); GP_STAGE(GP_SB(1, 1), b3 + hstepB, voffB); GP_STAGE(GP_SA(1, 0), a3, voffA);
;             GP_WAIT_V(8); GP_WAIT_L(0); GP_BAR; GP_MMA(1, 0, At, B0); GP_MMA(1, 1, At, B1); GP_BAR; GP_SCHED;
;         }
;         if (wr == 0) GP_BAR;
	s_add_i32 s34, s57, s12
	v_lshl_add_u64 v[214:215], v[214:215], 0, s[8:9]
	s_mov_b32 m0, s34
	ds_read_b128 v[160:163], v200 offset:49152
	ds_read_b128 v[164:167], v200 offset:50176
	ds_read_b128 v[168:171], v200 offset:51200
	ds_read_b128 v[172:175], v200 offset:52224
	ds_read_b128 v[190:193], v200 offset:53248
	ds_read_b128 v[202:205], v200 offset:54272
	ds_read_b128 v[206:209], v200 offset:55296
	ds_read_b128 v[210:213], v200 offset:56320
	global_load_lds_dwordx4 v[214:215], off
	s_add_i32 m0, s34, 0x2000
	s_add_u32 s28, s28, 0x40080
	v_lshl_add_u64 v[214:215], v[216:217], 0, s[8:9]
	s_addc_u32 s29, s29, 0
	s_add_i32 s34, s58, s12
	global_load_lds_dwordx4 v[214:215], off
	v_lshl_add_u64 v[214:215], s[28:29], 0, v[176:177]
	s_mov_b32 m0, s34
	s_nop 0
	global_load_lds_dwordx4 v[214:215], off
	v_lshl_add_u64 v[214:215], s[28:29], 0, v[178:179]
	s_add_i32 m0, s34, 0x2000
	s_nop 0
	global_load_lds_dwordx4 v[214:215], off
	v_lshl_add_u64 v[214:215], v[218:219], 0, s[8:9]
	s_mov_b32 m0, s47
	s_nop 0
	global_load_lds_dwordx4 v[214:215], off
	v_lshl_add_u64 v[214:215], v[220:221], 0, s[8:9]
	s_mov_b32 m0, s48
	s_nop 0
	global_load_lds_dwordx4 v[214:215], off
	s_waitcnt vmcnt(8)
	s_waitcnt lgkmcnt(0)
	s_barrier
	s_waitcnt lgkmcnt(0)
	v_mfma_f32_16x16x32_bf16 v[60:63], v[128:131], v[160:163], v[60:63]
	v_mfma_f32_16x16x32_bf16 v[56:59], v[136:139], v[160:163], v[56:59]
	v_mfma_f32_16x16x32_bf16 v[44:47], v[128:131], v[168:171], v[44:47]
	v_mfma_f32_16x16x32_bf16 v[40:43], v[136:139], v[168:171], v[40:43]
	v_mfma_f32_16x16x32_bf16 v[28:31], v[128:131], v[190:193], v[28:31]
	v_mfma_f32_16x16x32_bf16 v[24:27], v[136:139], v[190:193], v[24:27]
	v_mfma_f32_16x16x32_bf16 v[12:15], v[128:131], v[206:209], v[12:15]
	v_mfma_f32_16x16x32_bf16 v[8:11], v[136:139], v[206:209], v[8:11]
	v_mfma_f32_16x16x32_bf16 v[60:63], v[132:135], v[164:167], v[60:63]
	v_mfma_f32_16x16x32_bf16 v[56:59], v[140:143], v[164:167], v[56:59]
	v_mfma_f32_16x16x32_bf16 v[44:47], v[132:135], v[172:175], v[44:47]
	v_mfma_f32_16x16x32_bf16 v[40:43], v[140:143], v[172:175], v[40:43]
	v_mfma_f32_16x16x32_bf16 v[28:31], v[132:135], v[202:205], v[28:31]
	v_mfma_f32_16x16x32_bf16 v[24:27], v[140:143], v[202:205], v[24:27]
	v_mfma_f32_16x16x32_bf16 v[12:15], v[132:135], v[210:213], v[12:15]
	v_mfma_f32_16x16x32_bf16 v[8:11], v[140:143], v[210:213], v[8:11]
	v_mfma_f32_16x16x32_bf16 v[52:55], v[144:147], v[160:163], v[52:55]
	v_mfma_f32_16x16x32_bf16 v[48:51], v[152:155], v[160:163], v[48:51]
	v_mfma_f32_16x16x32_bf16 v[36:39], v[144:147], v[168:171], v[36:39]
	v_mfma_f32_16x16x32_bf16 v[32:35], v[152:155], v[168:171], v[32:35]
	v_mfma_f32_16x16x32_bf16 v[20:23], v[144:147], v[190:193], v[20:23]
	v_mfma_f32_16x16x32_bf16 v[16:19], v[152:155], v[190:193], v[16:19]
	v_mfma_f32_16x16x32_bf16 v[4:7], v[144:147], v[206:209], v[4:7]
	v_mfma_f32_16x16x32_bf16 v[0:3], v[152:155], v[206:209], v[0:3]
	v_mfma_f32_16x16x32_bf16 v[52:55], v[148:151], v[164:167], v[52:55]
	v_mfma_f32_16x16x32_bf16 v[48:51], v[156:159], v[164:167], v[48:51]
	v_mfma_f32_16x16x32_bf16 v[36:39], v[148:151], v[172:175], v[36:39]
	v_mfma_f32_16x16x32_bf16 v[32:35], v[156:159], v[172:175], v[32:35]
	v_mfma_f32_16x16x32_bf16 v[20:23], v[148:151], v[202:205], v[20:23]
	v_mfma_f32_16x16x32_bf16 v[16:19], v[156:159], v[202:205], v[16:19]
	v_mfma_f32_16x16x32_bf16 v[4:7], v[148:151], v[210:213], v[4:7]
	v_mfma_f32_16x16x32_bf16 v[0:3], v[156:159], v[210:213], v[0:3]
	s_barrier
	s_add_i32 s43, s43, 2
	s_add_u32 s40, s40, 0x100
	s_addc_u32 s41, s41, 0
	s_add_u32 s21, s21, 0x100
	s_addc_u32 s42, s42, 0
	s_cmp_gt_u32 s43, 13
	s_cbranch_scc0 .LBB0_629
	s_and_b64 vcc, exec, s[10:11]
	s_cbranch_vccz .LBB0_632
	s_barrier
